# streaming-store hint: nt on the 144 kraw_items output stores (KR is consumed only in P5)
# baseline (speedup 1.0000x reference)
; __device__ __forceinline__ void kraw_items(const Args& a, int gw, int NGW, int lane) {
;     ...
;     for (int it = gw; it < 192 * 32; it += NGW) {
;         const int pg = it >> 5, cgp = it & 31, p = pg * 64 + lane, c0 = cgp * 48;
;         float h[64];
; #pragma unroll
;         for (int q = 0; q < 16; ++q) { const f32x4 t = *(const f32x4*)(H3 + (size_t)p * 64 + 4 * q); h[4 * q] = t.x; h[4 * q + 1] = t.y; h[4 * q + 2] = t.z; h[4 * q + 3] = t.w; }
;         const int grp = p >= LP, tpos = p - grp * LP, L = grp ? LS : LP;
;         const float tt = (float)tpos * (1.0f / (float)(L - 1));
; #pragma unroll 1
;         for (int cb = 0; cb < 4; ++cb) {
;             const float* wr = a.in[I_FWOUT] + lane * 1536 + c0 + 12 * cb;
;             const f32x4 w0 = *(const f32x4*)(wr), w1 = *(const f32x4*)(wr + 4), w2 = *(const f32x4*)(wr + 8);
;             float wv[12] = {w0.x, w0.y, w0.z, w0.w, w1.x, w1.y, w1.z, w1.w, w2.x, w2.y, w2.z, w2.w};
.LBB0_116:
	s_cmp_eq_u32 s70, 0x100
	s_cbranch_scc0 .Lorig_kraw
	s_load_dwordx2 s[6:7], s[72:73], 0x90
	s_load_dwordx2 s[8:9], s[72:73], 0xe8
	v_and_b32_e32 v119, 63, v254
	v_and_b32_e32 v112, 31, v119
	v_lshrrev_b32_e32 v113, 5, v119
	v_lshlrev_b32_e32 v114, 8, v112
	v_lshl_add_u32 v114, v113, 7, v114
	v_mul_u32_u24_e32 v115, 0x30000, v113
	v_lshl_add_u32 v115, v112, 2, v115
	v_lshlrev_b32_e32 v118, 2, v113
	v_readfirstlane_b32 s16, v254
	s_nop 3
	s_lshl_b32 s30, s96, 3
	s_lshr_b32 s16, s16, 6
	s_add_i32 s16, s16, s30
	v_mov_b32_e32 v120, 0xc0447cbd
	s_waitcnt lgkmcnt(0)
	s_add_u32 s10, s8, 0x100000
	s_addc_u32 s11, s9, 0
	s_add_u32 s14, s8, 0x37000000
	s_addc_u32 s15, s9, 0
	s_mov_b32 s17, s16
	s_lshr_b32 s18, s17, 4
	s_and_b32 s19, s17, 15
	s_lshl_b32 s20, s18, 5
	s_mul_i32 s21, s19, 0x60
	s_lshl_b32 s30, s20, 8
	s_add_u32 s24, s10, s30
	s_addc_u32 s25, s11, 0
	global_load_dwordx4 v[0:3], v114, s[24:25] offset:0
	global_load_dwordx4 v[4:7], v114, s[24:25] offset:16
	global_load_dwordx4 v[8:11], v114, s[24:25] offset:32
	global_load_dwordx4 v[12:15], v114, s[24:25] offset:48
	global_load_dwordx4 v[16:19], v114, s[24:25] offset:64
	global_load_dwordx4 v[20:23], v114, s[24:25] offset:80
	global_load_dwordx4 v[24:27], v114, s[24:25] offset:96
	global_load_dwordx4 v[28:31], v114, s[24:25] offset:112
	s_add_i32 s30, s21, 0
	s_lshl_b32 s30, s30, 2
	s_add_u32 s26, s6, s30
	s_addc_u32 s27, s7, 0
	global_load_dword v64, v115, s[26:27]
	s_add_u32 s26, s26, 0x1800
	s_addc_u32 s27, s27, 0
	global_load_dword v65, v115, s[26:27]
	s_add_u32 s26, s26, 0x1800
	s_addc_u32 s27, s27, 0
	global_load_dword v66, v115, s[26:27]
	s_add_u32 s26, s26, 0x1800
	s_addc_u32 s27, s27, 0
	global_load_dword v67, v115, s[26:27]
	s_add_u32 s26, s26, 0x1800
	s_addc_u32 s27, s27, 0
	global_load_dword v68, v115, s[26:27]
	s_add_u32 s26, s26, 0x1800
	s_addc_u32 s27, s27, 0
	global_load_dword v69, v115, s[26:27]
	s_add_u32 s26, s26, 0x1800
	s_addc_u32 s27, s27, 0
	global_load_dword v70, v115, s[26:27]
	s_add_u32 s26, s26, 0x1800
	s_addc_u32 s27, s27, 0
	global_load_dword v71, v115, s[26:27]
	s_add_u32 s26, s26, 0x1800
	s_addc_u32 s27, s27, 0
	global_load_dword v72, v115, s[26:27]
	s_add_u32 s26, s26, 0x1800
	s_addc_u32 s27, s27, 0
	global_load_dword v73, v115, s[26:27]
	s_add_u32 s26, s26, 0x1800
	s_addc_u32 s27, s27, 0
	global_load_dword v74, v115, s[26:27]
	s_add_u32 s26, s26, 0x1800
	s_addc_u32 s27, s27, 0
	global_load_dword v75, v115, s[26:27]
	s_add_u32 s26, s26, 0x1800
	s_addc_u32 s27, s27, 0
	global_load_dword v76, v115, s[26:27]
	s_add_u32 s26, s26, 0x1800
	s_addc_u32 s27, s27, 0
	global_load_dword v77, v115, s[26:27]
	s_add_u32 s26, s26, 0x1800
	s_addc_u32 s27, s27, 0
	global_load_dword v78, v115, s[26:27]
	s_add_u32 s26, s26, 0x1800
	s_addc_u32 s27, s27, 0
	global_load_dword v79, v115, s[26:27]
	s_add_u32 s26, s26, 0x1800
	s_addc_u32 s27, s27, 0
	global_load_dword v80, v115, s[26:27]
	s_add_u32 s26, s26, 0x1800
	s_addc_u32 s27, s27, 0
	global_load_dword v81, v115, s[26:27]
	s_add_u32 s26, s26, 0x1800
	s_addc_u32 s27, s27, 0
	global_load_dword v82, v115, s[26:27]
	s_add_u32 s26, s26, 0x1800
	s_addc_u32 s27, s27, 0
	global_load_dword v83, v115, s[26:27]
	s_add_u32 s26, s26, 0x1800
	s_addc_u32 s27, s27, 0
	global_load_dword v84, v115, s[26:27]
	s_add_u32 s26, s26, 0x1800
	s_addc_u32 s27, s27, 0
	global_load_dword v85, v115, s[26:27]
	s_add_u32 s26, s26, 0x1800
	s_addc_u32 s27, s27, 0
	global_load_dword v86, v115, s[26:27]
	s_add_u32 s26, s26, 0x1800
	s_addc_u32 s27, s27, 0
	global_load_dword v87, v115, s[26:27]
	s_add_u32 s26, s26, 0x1800
	s_addc_u32 s27, s27, 0
	global_load_dword v88, v115, s[26:27]
	s_add_u32 s26, s26, 0x1800
	s_addc_u32 s27, s27, 0
	global_load_dword v89, v115, s[26:27]
	s_add_u32 s26, s26, 0x1800
	s_addc_u32 s27, s27, 0
	global_load_dword v90, v115, s[26:27]
	s_add_u32 s26, s26, 0x1800
	s_addc_u32 s27, s27, 0
	global_load_dword v91, v115, s[26:27]
	s_add_u32 s26, s26, 0x1800
	s_addc_u32 s27, s27, 0
	global_load_dword v92, v115, s[26:27]
	s_add_u32 s26, s26, 0x1800
	s_addc_u32 s27, s27, 0
	global_load_dword v93, v115, s[26:27]
	s_add_u32 s26, s26, 0x1800
	s_addc_u32 s27, s27, 0
	global_load_dword v94, v115, s[26:27]
	s_add_u32 s26, s26, 0x1800
	s_addc_u32 s27, s27, 0
	global_load_dword v95, v115, s[26:27]
	s_add_i32 s28, s21, 0
	s_sub_i32 s29, s28, 0x300
	s_cmp_ge_u32 s28, 0x300
	s_cselect_b32 s29, s29, s28
	s_mul_i32 s30, s28, 0xc000
	s_lshl_b32 s35, s20, 2
	s_add_u32 s30, s30, s35
	s_add_u32 s34, s14, s30
	s_addc_u32 s35, s15, 0
	s_mov_b32 s22, 0xb9000400
	s_cmp_ge_u32 s20, 0x2000
	s_cselect_b32 s22, 0xb9800801, s22
	s_and_b32 s30, s20, 0x1fff
	v_add_u32_e32 v119, s30, v112
	v_cvt_f32_u32_e32 v119, v119
	v_mul_f32_e32 v117, s22, v119
	s_add_i32 s30, s21, 32
	s_lshl_b32 s30, s30, 2
	s_add_u32 s26, s6, s30
	s_addc_u32 s27, s7, 0
	global_load_dword v128, v115, s[26:27]
	s_add_u32 s26, s26, 0x1800
	s_addc_u32 s27, s27, 0
	global_load_dword v129, v115, s[26:27]
	s_add_u32 s26, s26, 0x1800
	s_addc_u32 s27, s27, 0
	global_load_dword v130, v115, s[26:27]
	s_add_u32 s26, s26, 0x1800
	s_addc_u32 s27, s27, 0
	global_load_dword v131, v115, s[26:27]
	s_add_u32 s26, s26, 0x1800
	s_addc_u32 s27, s27, 0
	global_load_dword v132, v115, s[26:27]
	s_add_u32 s26, s26, 0x1800
	s_addc_u32 s27, s27, 0
	global_load_dword v133, v115, s[26:27]
	s_add_u32 s26, s26, 0x1800
	s_addc_u32 s27, s27, 0
	global_load_dword v134, v115, s[26:27]
	s_add_u32 s26, s26, 0x1800
	s_addc_u32 s27, s27, 0
	global_load_dword v135, v115, s[26:27]
	s_add_u32 s26, s26, 0x1800
	s_addc_u32 s27, s27, 0
	global_load_dword v136, v115, s[26:27]
	s_add_u32 s26, s26, 0x1800
	s_addc_u32 s27, s27, 0
; __device__ __forceinline__ void kraw_items(const Args& a, int gw, int NGW, int lane) {
;     ...
;             for (int ci = 0; ci < 12; ++ci) { const int c = c0 + 12 * cb + ci;
;                 float acc = 0.f;
; #pragma unroll
;                 for (int jj = 0; jj < 64; ++jj) acc += h[jj] * __builtin_bit_cast(float, __builtin_amdgcn_readlane(__builtin_bit_cast(int, wv[ci]), jj));
;                 const int cm = c % 768;
;                 const float delta = fabsf(-3.0701134573253945f + (float)cm * ((-15.350567286626973f + 3.0701134573253945f) / 767.0f));
;                 KR[(size_t)c * (LP + LS) + p] = acc * __expf(-tt * delta); }
	global_load_dword v137, v115, s[26:27]
	s_add_u32 s26, s26, 0x1800
	s_addc_u32 s27, s27, 0
	global_load_dword v138, v115, s[26:27]
	s_add_u32 s26, s26, 0x1800
	s_addc_u32 s27, s27, 0
	global_load_dword v139, v115, s[26:27]
	s_add_u32 s26, s26, 0x1800
	s_addc_u32 s27, s27, 0
	global_load_dword v140, v115, s[26:27]
	s_add_u32 s26, s26, 0x1800
	s_addc_u32 s27, s27, 0
	global_load_dword v141, v115, s[26:27]
	s_add_u32 s26, s26, 0x1800
	s_addc_u32 s27, s27, 0
	global_load_dword v142, v115, s[26:27]
	s_add_u32 s26, s26, 0x1800
	s_addc_u32 s27, s27, 0
	global_load_dword v143, v115, s[26:27]
	s_add_u32 s26, s26, 0x1800
	s_addc_u32 s27, s27, 0
	global_load_dword v144, v115, s[26:27]
	s_add_u32 s26, s26, 0x1800
	s_addc_u32 s27, s27, 0
	global_load_dword v145, v115, s[26:27]
	s_add_u32 s26, s26, 0x1800
	s_addc_u32 s27, s27, 0
	global_load_dword v146, v115, s[26:27]
	s_add_u32 s26, s26, 0x1800
	s_addc_u32 s27, s27, 0
	global_load_dword v147, v115, s[26:27]
	s_add_u32 s26, s26, 0x1800
	s_addc_u32 s27, s27, 0
	global_load_dword v148, v115, s[26:27]
	s_add_u32 s26, s26, 0x1800
	s_addc_u32 s27, s27, 0
	global_load_dword v149, v115, s[26:27]
	s_add_u32 s26, s26, 0x1800
	s_addc_u32 s27, s27, 0
	global_load_dword v150, v115, s[26:27]
	s_add_u32 s26, s26, 0x1800
	s_addc_u32 s27, s27, 0
	global_load_dword v151, v115, s[26:27]
	s_add_u32 s26, s26, 0x1800
	s_addc_u32 s27, s27, 0
	global_load_dword v152, v115, s[26:27]
	s_add_u32 s26, s26, 0x1800
	s_addc_u32 s27, s27, 0
	global_load_dword v153, v115, s[26:27]
	s_add_u32 s26, s26, 0x1800
	s_addc_u32 s27, s27, 0
	global_load_dword v154, v115, s[26:27]
	s_add_u32 s26, s26, 0x1800
	s_addc_u32 s27, s27, 0
	global_load_dword v155, v115, s[26:27]
	s_add_u32 s26, s26, 0x1800
	s_addc_u32 s27, s27, 0
	global_load_dword v156, v115, s[26:27]
	s_add_u32 s26, s26, 0x1800
	s_addc_u32 s27, s27, 0
	global_load_dword v157, v115, s[26:27]
	s_add_u32 s26, s26, 0x1800
	s_addc_u32 s27, s27, 0
	global_load_dword v158, v115, s[26:27]
	s_add_u32 s26, s26, 0x1800
	s_addc_u32 s27, s27, 0
	global_load_dword v159, v115, s[26:27]
	s_waitcnt vmcnt(32)
	v_mfma_f32_32x32x2_f32 v[96:111], v64, v0, 0
	v_mfma_f32_32x32x2_f32 v[96:111], v65, v1, v[96:111]
	v_mfma_f32_32x32x2_f32 v[96:111], v66, v2, v[96:111]
	v_mfma_f32_32x32x2_f32 v[96:111], v67, v3, v[96:111]
	v_mfma_f32_32x32x2_f32 v[96:111], v68, v4, v[96:111]
	v_mfma_f32_32x32x2_f32 v[96:111], v69, v5, v[96:111]
	v_mfma_f32_32x32x2_f32 v[96:111], v70, v6, v[96:111]
	v_mfma_f32_32x32x2_f32 v[96:111], v71, v7, v[96:111]
	v_mfma_f32_32x32x2_f32 v[96:111], v72, v8, v[96:111]
	v_mfma_f32_32x32x2_f32 v[96:111], v73, v9, v[96:111]
	v_mfma_f32_32x32x2_f32 v[96:111], v74, v10, v[96:111]
	v_mfma_f32_32x32x2_f32 v[96:111], v75, v11, v[96:111]
	v_mfma_f32_32x32x2_f32 v[96:111], v76, v12, v[96:111]
	v_mfma_f32_32x32x2_f32 v[96:111], v77, v13, v[96:111]
	v_mfma_f32_32x32x2_f32 v[96:111], v78, v14, v[96:111]
	v_mfma_f32_32x32x2_f32 v[96:111], v79, v15, v[96:111]
	v_mfma_f32_32x32x2_f32 v[96:111], v80, v16, v[96:111]
	v_mfma_f32_32x32x2_f32 v[96:111], v81, v17, v[96:111]
	v_mfma_f32_32x32x2_f32 v[96:111], v82, v18, v[96:111]
	v_mfma_f32_32x32x2_f32 v[96:111], v83, v19, v[96:111]
	v_mfma_f32_32x32x2_f32 v[96:111], v84, v20, v[96:111]
	v_mfma_f32_32x32x2_f32 v[96:111], v85, v21, v[96:111]
	v_mfma_f32_32x32x2_f32 v[96:111], v86, v22, v[96:111]
	v_mfma_f32_32x32x2_f32 v[96:111], v87, v23, v[96:111]
	v_mfma_f32_32x32x2_f32 v[96:111], v88, v24, v[96:111]
	v_mfma_f32_32x32x2_f32 v[96:111], v89, v25, v[96:111]
	v_mfma_f32_32x32x2_f32 v[96:111], v90, v26, v[96:111]
	v_mfma_f32_32x32x2_f32 v[96:111], v91, v27, v[96:111]
	v_mfma_f32_32x32x2_f32 v[96:111], v92, v28, v[96:111]
	v_mfma_f32_32x32x2_f32 v[96:111], v93, v29, v[96:111]
	v_mfma_f32_32x32x2_f32 v[96:111], v94, v30, v[96:111]
	v_mfma_f32_32x32x2_f32 v[96:111], v95, v31, v[96:111]
	s_add_i32 s30, s29, 0
	v_add_u32_e32 v119, s30, v118
	v_cvt_f32_u32_e32 v119, v119
	v_fmamk_f32 v119, v119, 0xbc83298c, v120
	v_mul_f32_e64 v119, v117, |v119|
	v_mul_f32_e32 v119, 0x3fb8aa3b, v119
	v_exp_f32_e32 v160, v119
	s_add_i32 s30, s29, 1
	v_add_u32_e32 v119, s30, v118
	v_cvt_f32_u32_e32 v119, v119
	v_fmamk_f32 v119, v119, 0xbc83298c, v120
	v_mul_f32_e64 v119, v117, |v119|
	v_mul_f32_e32 v119, 0x3fb8aa3b, v119
	v_exp_f32_e32 v161, v119
	s_add_i32 s30, s29, 2
	v_add_u32_e32 v119, s30, v118
	v_cvt_f32_u32_e32 v119, v119
	v_fmamk_f32 v119, v119, 0xbc83298c, v120
	v_mul_f32_e64 v119, v117, |v119|
	v_mul_f32_e32 v119, 0x3fb8aa3b, v119
	v_exp_f32_e32 v162, v119
	s_add_i32 s30, s29, 3
	v_add_u32_e32 v119, s30, v118
	v_cvt_f32_u32_e32 v119, v119
	v_fmamk_f32 v119, v119, 0xbc83298c, v120
	v_mul_f32_e64 v119, v117, |v119|
	v_mul_f32_e32 v119, 0x3fb8aa3b, v119
	v_exp_f32_e32 v163, v119
	s_add_i32 s30, s29, 8
	v_add_u32_e32 v119, s30, v118
	v_cvt_f32_u32_e32 v119, v119
	v_fmamk_f32 v119, v119, 0xbc83298c, v120
	v_mul_f32_e64 v119, v117, |v119|
	v_mul_f32_e32 v119, 0x3fb8aa3b, v119
	v_exp_f32_e32 v164, v119
	s_add_i32 s30, s29, 9
	v_add_u32_e32 v119, s30, v118
	v_cvt_f32_u32_e32 v119, v119
	v_fmamk_f32 v119, v119, 0xbc83298c, v120
	v_mul_f32_e64 v119, v117, |v119|
	v_mul_f32_e32 v119, 0x3fb8aa3b, v119
	v_exp_f32_e32 v165, v119
	s_add_i32 s30, s29, 10
	v_add_u32_e32 v119, s30, v118
	v_cvt_f32_u32_e32 v119, v119
	v_fmamk_f32 v119, v119, 0xbc83298c, v120
	v_mul_f32_e64 v119, v117, |v119|
	v_mul_f32_e32 v119, 0x3fb8aa3b, v119
	v_exp_f32_e32 v166, v119
	s_add_i32 s30, s29, 11
	v_add_u32_e32 v119, s30, v118
	v_cvt_f32_u32_e32 v119, v119
	v_fmamk_f32 v119, v119, 0xbc83298c, v120
	v_mul_f32_e64 v119, v117, |v119|
	v_mul_f32_e32 v119, 0x3fb8aa3b, v119
	v_exp_f32_e32 v167, v119
	s_add_i32 s30, s29, 16
; __device__ __forceinline__ void kraw_items(const Args& a, int gw, int NGW, int lane) {
;     ...
;                 for (int jj = 0; jj < 64; ++jj) acc += h[jj] * __builtin_bit_cast(float, __builtin_amdgcn_readlane(__builtin_bit_cast(int, wv[ci]), jj));
;                 const int cm = c % 768;
;                 const float delta = fabsf(-3.0701134573253945f + (float)cm * ((-15.350567286626973f + 3.0701134573253945f) / 767.0f));
;                 KR[(size_t)c * (LP + LS) + p] = acc * __expf(-tt * delta); }
	v_add_u32_e32 v119, s30, v118
	v_cvt_f32_u32_e32 v119, v119
	v_fmamk_f32 v119, v119, 0xbc83298c, v120
	v_mul_f32_e64 v119, v117, |v119|
	v_mul_f32_e32 v119, 0x3fb8aa3b, v119
	v_exp_f32_e32 v168, v119
	s_add_i32 s30, s29, 17
	v_add_u32_e32 v119, s30, v118
	v_cvt_f32_u32_e32 v119, v119
	v_fmamk_f32 v119, v119, 0xbc83298c, v120
	v_mul_f32_e64 v119, v117, |v119|
	v_mul_f32_e32 v119, 0x3fb8aa3b, v119
	v_exp_f32_e32 v169, v119
	s_add_i32 s30, s29, 18
	v_add_u32_e32 v119, s30, v118
	v_cvt_f32_u32_e32 v119, v119
	v_fmamk_f32 v119, v119, 0xbc83298c, v120
	v_mul_f32_e64 v119, v117, |v119|
	v_mul_f32_e32 v119, 0x3fb8aa3b, v119
	v_exp_f32_e32 v170, v119
	s_add_i32 s30, s29, 19
	v_add_u32_e32 v119, s30, v118
	v_cvt_f32_u32_e32 v119, v119
	v_fmamk_f32 v119, v119, 0xbc83298c, v120
	v_mul_f32_e64 v119, v117, |v119|
	v_mul_f32_e32 v119, 0x3fb8aa3b, v119
	v_exp_f32_e32 v171, v119
	s_add_i32 s30, s29, 24
	v_add_u32_e32 v119, s30, v118
	v_cvt_f32_u32_e32 v119, v119
	v_fmamk_f32 v119, v119, 0xbc83298c, v120
	v_mul_f32_e64 v119, v117, |v119|
	v_mul_f32_e32 v119, 0x3fb8aa3b, v119
	v_exp_f32_e32 v172, v119
	s_add_i32 s30, s29, 25
	v_add_u32_e32 v119, s30, v118
	v_cvt_f32_u32_e32 v119, v119
	v_fmamk_f32 v119, v119, 0xbc83298c, v120
	v_mul_f32_e64 v119, v117, |v119|
	v_mul_f32_e32 v119, 0x3fb8aa3b, v119
	v_exp_f32_e32 v173, v119
	s_add_i32 s30, s29, 26
	v_add_u32_e32 v119, s30, v118
	v_cvt_f32_u32_e32 v119, v119
	v_fmamk_f32 v119, v119, 0xbc83298c, v120
	v_mul_f32_e64 v119, v117, |v119|
	v_mul_f32_e32 v119, 0x3fb8aa3b, v119
	v_exp_f32_e32 v174, v119
	s_add_i32 s30, s29, 27
	v_add_u32_e32 v119, s30, v118
	v_cvt_f32_u32_e32 v119, v119
	v_fmamk_f32 v119, v119, 0xbc83298c, v120
	v_mul_f32_e64 v119, v117, |v119|
	v_mul_f32_e32 v119, 0x3fb8aa3b, v119
	v_exp_f32_e32 v175, v119
	s_nop 7
	v_mul_f32_e32 v176, v96, v160
	s_mov_b64 s[36:37], s[34:35]
	global_store_dword v115, v176, s[36:37] nt
	v_mul_f32_e32 v177, v97, v161
	s_add_u32 s36, s34, 0xc000
	s_addc_u32 s37, s35, 0
	global_store_dword v115, v177, s[36:37] nt
	v_mul_f32_e32 v178, v98, v162
	s_add_u32 s36, s34, 0x18000
	s_addc_u32 s37, s35, 0
	global_store_dword v115, v178, s[36:37] nt
	v_mul_f32_e32 v179, v99, v163
	s_add_u32 s36, s34, 0x24000
	s_addc_u32 s37, s35, 0
	global_store_dword v115, v179, s[36:37] nt
	v_mul_f32_e32 v180, v100, v164
	s_add_u32 s36, s34, 0x60000
	s_addc_u32 s37, s35, 0
	global_store_dword v115, v180, s[36:37] nt
	v_mul_f32_e32 v181, v101, v165
	s_add_u32 s36, s34, 0x6c000
	s_addc_u32 s37, s35, 0
	global_store_dword v115, v181, s[36:37] nt
	v_mul_f32_e32 v182, v102, v166
	s_add_u32 s36, s34, 0x78000
	s_addc_u32 s37, s35, 0
	global_store_dword v115, v182, s[36:37] nt
	v_mul_f32_e32 v183, v103, v167
	s_add_u32 s36, s34, 0x84000
	s_addc_u32 s37, s35, 0
	global_store_dword v115, v183, s[36:37] nt
	v_mul_f32_e32 v184, v104, v168
	s_add_u32 s36, s34, 0xc0000
	s_addc_u32 s37, s35, 0
	global_store_dword v115, v184, s[36:37] nt
	v_mul_f32_e32 v185, v105, v169
	s_add_u32 s36, s34, 0xcc000
	s_addc_u32 s37, s35, 0
	global_store_dword v115, v185, s[36:37] nt
	v_mul_f32_e32 v186, v106, v170
	s_add_u32 s36, s34, 0xd8000
	s_addc_u32 s37, s35, 0
	global_store_dword v115, v186, s[36:37] nt
	v_mul_f32_e32 v187, v107, v171
	s_add_u32 s36, s34, 0xe4000
	s_addc_u32 s37, s35, 0
	global_store_dword v115, v187, s[36:37] nt
	v_mul_f32_e32 v188, v108, v172
	s_add_u32 s36, s34, 0x120000
	s_addc_u32 s37, s35, 0
	global_store_dword v115, v188, s[36:37] nt
	v_mul_f32_e32 v189, v109, v173
	s_add_u32 s36, s34, 0x12c000
	s_addc_u32 s37, s35, 0
	global_store_dword v115, v189, s[36:37] nt
	v_mul_f32_e32 v190, v110, v174
	s_add_u32 s36, s34, 0x138000
	s_addc_u32 s37, s35, 0
	global_store_dword v115, v190, s[36:37] nt
	v_mul_f32_e32 v191, v111, v175
	s_add_u32 s36, s34, 0x144000
	s_addc_u32 s37, s35, 0
	global_store_dword v115, v191, s[36:37] nt
	s_add_i32 s28, s21, 32
	s_sub_i32 s29, s28, 0x300
	s_cmp_ge_u32 s28, 0x300
	s_cselect_b32 s29, s29, s28
	s_mul_i32 s30, s28, 0xc000
	s_lshl_b32 s35, s20, 2
	s_add_u32 s30, s30, s35
	s_add_u32 s34, s14, s30
	s_addc_u32 s35, s15, 0
	s_add_i32 s30, s21, 64
	s_lshl_b32 s30, s30, 2
	s_add_u32 s26, s6, s30
	s_addc_u32 s27, s7, 0
	global_load_dword v64, v115, s[26:27]
	s_add_u32 s26, s26, 0x1800
	s_addc_u32 s27, s27, 0
	global_load_dword v65, v115, s[26:27]
	s_add_u32 s26, s26, 0x1800
	s_addc_u32 s27, s27, 0
	global_load_dword v66, v115, s[26:27]
	s_add_u32 s26, s26, 0x1800
	s_addc_u32 s27, s27, 0
	global_load_dword v67, v115, s[26:27]
	s_add_u32 s26, s26, 0x1800
	s_addc_u32 s27, s27, 0
	global_load_dword v68, v115, s[26:27]
	s_add_u32 s26, s26, 0x1800
	s_addc_u32 s27, s27, 0
	global_load_dword v69, v115, s[26:27]
	s_add_u32 s26, s26, 0x1800
	s_addc_u32 s27, s27, 0
	global_load_dword v70, v115, s[26:27]
	s_add_u32 s26, s26, 0x1800
	s_addc_u32 s27, s27, 0
	global_load_dword v71, v115, s[26:27]
	s_add_u32 s26, s26, 0x1800
	s_addc_u32 s27, s27, 0
	global_load_dword v72, v115, s[26:27]
	s_add_u32 s26, s26, 0x1800
	s_addc_u32 s27, s27, 0
	global_load_dword v73, v115, s[26:27]
	s_add_u32 s26, s26, 0x1800
	s_addc_u32 s27, s27, 0
	global_load_dword v74, v115, s[26:27]
	s_add_u32 s26, s26, 0x1800
	s_addc_u32 s27, s27, 0
	global_load_dword v75, v115, s[26:27]
	s_add_u32 s26, s26, 0x1800
	s_addc_u32 s27, s27, 0
	global_load_dword v76, v115, s[26:27]
	s_add_u32 s26, s26, 0x1800
	s_addc_u32 s27, s27, 0
	global_load_dword v77, v115, s[26:27]
	s_add_u32 s26, s26, 0x1800
	s_addc_u32 s27, s27, 0
	global_load_dword v78, v115, s[26:27]
	s_add_u32 s26, s26, 0x1800
	s_addc_u32 s27, s27, 0
	global_load_dword v79, v115, s[26:27]
	s_add_u32 s26, s26, 0x1800
	s_addc_u32 s27, s27, 0
	global_load_dword v80, v115, s[26:27]
	s_add_u32 s26, s26, 0x1800
	s_addc_u32 s27, s27, 0
	global_load_dword v81, v115, s[26:27]
	s_add_u32 s26, s26, 0x1800
	s_addc_u32 s27, s27, 0
	global_load_dword v82, v115, s[26:27]
	s_add_u32 s26, s26, 0x1800
	s_addc_u32 s27, s27, 0
	global_load_dword v83, v115, s[26:27]
	s_add_u32 s26, s26, 0x1800
	s_addc_u32 s27, s27, 0
	global_load_dword v84, v115, s[26:27]
	s_add_u32 s26, s26, 0x1800
	s_addc_u32 s27, s27, 0
	global_load_dword v85, v115, s[26:27]
	s_add_u32 s26, s26, 0x1800
	s_addc_u32 s27, s27, 0
	global_load_dword v86, v115, s[26:27]
	s_add_u32 s26, s26, 0x1800
	s_addc_u32 s27, s27, 0
	global_load_dword v87, v115, s[26:27]
	s_add_u32 s26, s26, 0x1800
	s_addc_u32 s27, s27, 0
	global_load_dword v88, v115, s[26:27]
	s_add_u32 s26, s26, 0x1800
	s_addc_u32 s27, s27, 0
	global_load_dword v89, v115, s[26:27]
	s_add_u32 s26, s26, 0x1800
	s_addc_u32 s27, s27, 0
	global_load_dword v90, v115, s[26:27]
	s_add_u32 s26, s26, 0x1800
	s_addc_u32 s27, s27, 0
	global_load_dword v91, v115, s[26:27]
	s_add_u32 s26, s26, 0x1800
	s_addc_u32 s27, s27, 0
	global_load_dword v92, v115, s[26:27]
	s_add_u32 s26, s26, 0x1800
	s_addc_u32 s27, s27, 0
	global_load_dword v93, v115, s[26:27]
	s_add_u32 s26, s26, 0x1800
	s_addc_u32 s27, s27, 0
	global_load_dword v94, v115, s[26:27]
	s_add_u32 s26, s26, 0x1800
	s_addc_u32 s27, s27, 0
	global_load_dword v95, v115, s[26:27]
	s_waitcnt vmcnt(48)
; __device__ __forceinline__ void kraw_items(const Args& a, int gw, int NGW, int lane) {
;     ...
;             for (int ci = 0; ci < 12; ++ci) { const int c = c0 + 12 * cb + ci;
;                 float acc = 0.f;
; #pragma unroll
;                 for (int jj = 0; jj < 64; ++jj) acc += h[jj] * __builtin_bit_cast(float, __builtin_amdgcn_readlane(__builtin_bit_cast(int, wv[ci]), jj));
;                 const int cm = c % 768;
;                 const float delta = fabsf(-3.0701134573253945f + (float)cm * ((-15.350567286626973f + 3.0701134573253945f) / 767.0f));
;                 KR[(size_t)c * (LP + LS) + p] = acc * __expf(-tt * delta); }
	v_mfma_f32_32x32x2_f32 v[96:111], v128, v0, 0
	v_mfma_f32_32x32x2_f32 v[96:111], v129, v1, v[96:111]
	v_mfma_f32_32x32x2_f32 v[96:111], v130, v2, v[96:111]
	v_mfma_f32_32x32x2_f32 v[96:111], v131, v3, v[96:111]
	v_mfma_f32_32x32x2_f32 v[96:111], v132, v4, v[96:111]
	v_mfma_f32_32x32x2_f32 v[96:111], v133, v5, v[96:111]
	v_mfma_f32_32x32x2_f32 v[96:111], v134, v6, v[96:111]
	v_mfma_f32_32x32x2_f32 v[96:111], v135, v7, v[96:111]
	v_mfma_f32_32x32x2_f32 v[96:111], v136, v8, v[96:111]
	v_mfma_f32_32x32x2_f32 v[96:111], v137, v9, v[96:111]
	v_mfma_f32_32x32x2_f32 v[96:111], v138, v10, v[96:111]
	v_mfma_f32_32x32x2_f32 v[96:111], v139, v11, v[96:111]
	v_mfma_f32_32x32x2_f32 v[96:111], v140, v12, v[96:111]
	v_mfma_f32_32x32x2_f32 v[96:111], v141, v13, v[96:111]
	v_mfma_f32_32x32x2_f32 v[96:111], v142, v14, v[96:111]
	v_mfma_f32_32x32x2_f32 v[96:111], v143, v15, v[96:111]
	v_mfma_f32_32x32x2_f32 v[96:111], v144, v16, v[96:111]
	v_mfma_f32_32x32x2_f32 v[96:111], v145, v17, v[96:111]
	v_mfma_f32_32x32x2_f32 v[96:111], v146, v18, v[96:111]
	v_mfma_f32_32x32x2_f32 v[96:111], v147, v19, v[96:111]
	v_mfma_f32_32x32x2_f32 v[96:111], v148, v20, v[96:111]
	v_mfma_f32_32x32x2_f32 v[96:111], v149, v21, v[96:111]
	v_mfma_f32_32x32x2_f32 v[96:111], v150, v22, v[96:111]
	v_mfma_f32_32x32x2_f32 v[96:111], v151, v23, v[96:111]
	v_mfma_f32_32x32x2_f32 v[96:111], v152, v24, v[96:111]
	v_mfma_f32_32x32x2_f32 v[96:111], v153, v25, v[96:111]
	v_mfma_f32_32x32x2_f32 v[96:111], v154, v26, v[96:111]
	v_mfma_f32_32x32x2_f32 v[96:111], v155, v27, v[96:111]
	v_mfma_f32_32x32x2_f32 v[96:111], v156, v28, v[96:111]
	v_mfma_f32_32x32x2_f32 v[96:111], v157, v29, v[96:111]
	v_mfma_f32_32x32x2_f32 v[96:111], v158, v30, v[96:111]
	v_mfma_f32_32x32x2_f32 v[96:111], v159, v31, v[96:111]
	s_add_i32 s30, s29, 0
	v_add_u32_e32 v119, s30, v118
	v_cvt_f32_u32_e32 v119, v119
	v_fmamk_f32 v119, v119, 0xbc83298c, v120
	v_mul_f32_e64 v119, v117, |v119|
	v_mul_f32_e32 v119, 0x3fb8aa3b, v119
	v_exp_f32_e32 v160, v119
	s_add_i32 s30, s29, 1
	v_add_u32_e32 v119, s30, v118
	v_cvt_f32_u32_e32 v119, v119
	v_fmamk_f32 v119, v119, 0xbc83298c, v120
	v_mul_f32_e64 v119, v117, |v119|
	v_mul_f32_e32 v119, 0x3fb8aa3b, v119
	v_exp_f32_e32 v161, v119
	s_add_i32 s30, s29, 2
	v_add_u32_e32 v119, s30, v118
	v_cvt_f32_u32_e32 v119, v119
	v_fmamk_f32 v119, v119, 0xbc83298c, v120
	v_mul_f32_e64 v119, v117, |v119|
	v_mul_f32_e32 v119, 0x3fb8aa3b, v119
	v_exp_f32_e32 v162, v119
	s_add_i32 s30, s29, 3
	v_add_u32_e32 v119, s30, v118
	v_cvt_f32_u32_e32 v119, v119
	v_fmamk_f32 v119, v119, 0xbc83298c, v120
	v_mul_f32_e64 v119, v117, |v119|
	v_mul_f32_e32 v119, 0x3fb8aa3b, v119
	v_exp_f32_e32 v163, v119
	s_add_i32 s30, s29, 8
	v_add_u32_e32 v119, s30, v118
	v_cvt_f32_u32_e32 v119, v119
	v_fmamk_f32 v119, v119, 0xbc83298c, v120
	v_mul_f32_e64 v119, v117, |v119|
	v_mul_f32_e32 v119, 0x3fb8aa3b, v119
	v_exp_f32_e32 v164, v119
	s_add_i32 s30, s29, 9
	v_add_u32_e32 v119, s30, v118
	v_cvt_f32_u32_e32 v119, v119
	v_fmamk_f32 v119, v119, 0xbc83298c, v120
	v_mul_f32_e64 v119, v117, |v119|
	v_mul_f32_e32 v119, 0x3fb8aa3b, v119
	v_exp_f32_e32 v165, v119
	s_add_i32 s30, s29, 10
	v_add_u32_e32 v119, s30, v118
	v_cvt_f32_u32_e32 v119, v119
	v_fmamk_f32 v119, v119, 0xbc83298c, v120
	v_mul_f32_e64 v119, v117, |v119|
	v_mul_f32_e32 v119, 0x3fb8aa3b, v119
	v_exp_f32_e32 v166, v119
	s_add_i32 s30, s29, 11
	v_add_u32_e32 v119, s30, v118
	v_cvt_f32_u32_e32 v119, v119
	v_fmamk_f32 v119, v119, 0xbc83298c, v120
	v_mul_f32_e64 v119, v117, |v119|
	v_mul_f32_e32 v119, 0x3fb8aa3b, v119
	v_exp_f32_e32 v167, v119
	s_add_i32 s30, s29, 16
	v_add_u32_e32 v119, s30, v118
	v_cvt_f32_u32_e32 v119, v119
	v_fmamk_f32 v119, v119, 0xbc83298c, v120
	v_mul_f32_e64 v119, v117, |v119|
	v_mul_f32_e32 v119, 0x3fb8aa3b, v119
	v_exp_f32_e32 v168, v119
	s_add_i32 s30, s29, 17
	v_add_u32_e32 v119, s30, v118
	v_cvt_f32_u32_e32 v119, v119
	v_fmamk_f32 v119, v119, 0xbc83298c, v120
	v_mul_f32_e64 v119, v117, |v119|
	v_mul_f32_e32 v119, 0x3fb8aa3b, v119
	v_exp_f32_e32 v169, v119
	s_add_i32 s30, s29, 18
	v_add_u32_e32 v119, s30, v118
	v_cvt_f32_u32_e32 v119, v119
	v_fmamk_f32 v119, v119, 0xbc83298c, v120
	v_mul_f32_e64 v119, v117, |v119|
	v_mul_f32_e32 v119, 0x3fb8aa3b, v119
	v_exp_f32_e32 v170, v119
	s_add_i32 s30, s29, 19
	v_add_u32_e32 v119, s30, v118
	v_cvt_f32_u32_e32 v119, v119
	v_fmamk_f32 v119, v119, 0xbc83298c, v120
	v_mul_f32_e64 v119, v117, |v119|
	v_mul_f32_e32 v119, 0x3fb8aa3b, v119
	v_exp_f32_e32 v171, v119
	s_add_i32 s30, s29, 24
	v_add_u32_e32 v119, s30, v118
	v_cvt_f32_u32_e32 v119, v119
	v_fmamk_f32 v119, v119, 0xbc83298c, v120
	v_mul_f32_e64 v119, v117, |v119|
	v_mul_f32_e32 v119, 0x3fb8aa3b, v119
	v_exp_f32_e32 v172, v119
	s_add_i32 s30, s29, 25
	v_add_u32_e32 v119, s30, v118
	v_cvt_f32_u32_e32 v119, v119
	v_fmamk_f32 v119, v119, 0xbc83298c, v120
	v_mul_f32_e64 v119, v117, |v119|
	v_mul_f32_e32 v119, 0x3fb8aa3b, v119
	v_exp_f32_e32 v173, v119
	s_add_i32 s30, s29, 26
	v_add_u32_e32 v119, s30, v118
	v_cvt_f32_u32_e32 v119, v119
	v_fmamk_f32 v119, v119, 0xbc83298c, v120
	v_mul_f32_e64 v119, v117, |v119|
	v_mul_f32_e32 v119, 0x3fb8aa3b, v119
	v_exp_f32_e32 v174, v119
	s_add_i32 s30, s29, 27
	v_add_u32_e32 v119, s30, v118
	v_cvt_f32_u32_e32 v119, v119
	v_fmamk_f32 v119, v119, 0xbc83298c, v120
	v_mul_f32_e64 v119, v117, |v119|
	v_mul_f32_e32 v119, 0x3fb8aa3b, v119
	v_exp_f32_e32 v175, v119
	s_nop 7
	v_mul_f32_e32 v176, v96, v160
	s_mov_b64 s[36:37], s[34:35]
	global_store_dword v115, v176, s[36:37] nt
	v_mul_f32_e32 v177, v97, v161
	s_add_u32 s36, s34, 0xc000
	s_addc_u32 s37, s35, 0
	global_store_dword v115, v177, s[36:37] nt
	v_mul_f32_e32 v178, v98, v162
; __device__ __forceinline__ void kraw_items(const Args& a, int gw, int NGW, int lane) {
;     ...
;     for (int it = gw; it < 192 * 32; it += NGW) {
;         const int pg = it >> 5, cgp = it & 31, p = pg * 64 + lane, c0 = cgp * 48;
;         float h[64];
; #pragma unroll
;         for (int q = 0; q < 16; ++q) { const f32x4 t = *(const f32x4*)(H3 + (size_t)p * 64 + 4 * q); h[4 * q] = t.x; h[4 * q + 1] = t.y; h[4 * q + 2] = t.z; h[4 * q + 3] = t.w; }
;         const int grp = p >= LP, tpos = p - grp * LP, L = grp ? LS : LP;
;     ...
;                 KR[(size_t)c * (LP + LS) + p] = acc * __expf(-tt * delta); }
	s_add_u32 s36, s34, 0x18000
	s_addc_u32 s37, s35, 0
	global_store_dword v115, v178, s[36:37] nt
	v_mul_f32_e32 v179, v99, v163
	s_add_u32 s36, s34, 0x24000
	s_addc_u32 s37, s35, 0
	global_store_dword v115, v179, s[36:37] nt
	v_mul_f32_e32 v180, v100, v164
	s_add_u32 s36, s34, 0x60000
	s_addc_u32 s37, s35, 0
	global_store_dword v115, v180, s[36:37] nt
	v_mul_f32_e32 v181, v101, v165
	s_add_u32 s36, s34, 0x6c000
	s_addc_u32 s37, s35, 0
	global_store_dword v115, v181, s[36:37] nt
	v_mul_f32_e32 v182, v102, v166
	s_add_u32 s36, s34, 0x78000
	s_addc_u32 s37, s35, 0
	global_store_dword v115, v182, s[36:37] nt
	v_mul_f32_e32 v183, v103, v167
	s_add_u32 s36, s34, 0x84000
	s_addc_u32 s37, s35, 0
	global_store_dword v115, v183, s[36:37] nt
	v_mul_f32_e32 v184, v104, v168
	s_add_u32 s36, s34, 0xc0000
	s_addc_u32 s37, s35, 0
	global_store_dword v115, v184, s[36:37] nt
	v_mul_f32_e32 v185, v105, v169
	s_add_u32 s36, s34, 0xcc000
	s_addc_u32 s37, s35, 0
	global_store_dword v115, v185, s[36:37] nt
	v_mul_f32_e32 v186, v106, v170
	s_add_u32 s36, s34, 0xd8000
	s_addc_u32 s37, s35, 0
	global_store_dword v115, v186, s[36:37] nt
	v_mul_f32_e32 v187, v107, v171
	s_add_u32 s36, s34, 0xe4000
	s_addc_u32 s37, s35, 0
	global_store_dword v115, v187, s[36:37] nt
	v_mul_f32_e32 v188, v108, v172
	s_add_u32 s36, s34, 0x120000
	s_addc_u32 s37, s35, 0
	global_store_dword v115, v188, s[36:37] nt
	v_mul_f32_e32 v189, v109, v173
	s_add_u32 s36, s34, 0x12c000
	s_addc_u32 s37, s35, 0
	global_store_dword v115, v189, s[36:37] nt
	v_mul_f32_e32 v190, v110, v174
	s_add_u32 s36, s34, 0x138000
	s_addc_u32 s37, s35, 0
	global_store_dword v115, v190, s[36:37] nt
	v_mul_f32_e32 v191, v111, v175
	s_add_u32 s36, s34, 0x144000
	s_addc_u32 s37, s35, 0
	global_store_dword v115, v191, s[36:37] nt
	s_add_i32 s28, s21, 64
	s_sub_i32 s29, s28, 0x300
	s_cmp_ge_u32 s28, 0x300
	s_cselect_b32 s29, s29, s28
	s_mul_i32 s30, s28, 0xc000
	s_lshl_b32 s35, s20, 2
	s_add_u32 s30, s30, s35
	s_add_u32 s34, s14, s30
	s_addc_u32 s35, s15, 0
	s_add_i32 s17, s16, 0x800
	s_lshr_b32 s18, s17, 4
	s_and_b32 s19, s17, 15
	s_lshl_b32 s20, s18, 5
	s_mul_i32 s21, s19, 0x60
	s_lshl_b32 s30, s20, 8
	s_add_u32 s24, s10, s30
	s_addc_u32 s25, s11, 0
	global_load_dwordx4 v[32:35], v114, s[24:25] offset:0
	global_load_dwordx4 v[36:39], v114, s[24:25] offset:16
	global_load_dwordx4 v[40:43], v114, s[24:25] offset:32
	global_load_dwordx4 v[44:47], v114, s[24:25] offset:48
	global_load_dwordx4 v[48:51], v114, s[24:25] offset:64
	global_load_dwordx4 v[52:55], v114, s[24:25] offset:80
	global_load_dwordx4 v[56:59], v114, s[24:25] offset:96
	global_load_dwordx4 v[60:63], v114, s[24:25] offset:112
	s_add_i32 s30, s21, 0
	s_lshl_b32 s30, s30, 2
	s_add_u32 s26, s6, s30
	s_addc_u32 s27, s7, 0
	global_load_dword v128, v115, s[26:27]
	s_add_u32 s26, s26, 0x1800
	s_addc_u32 s27, s27, 0
	global_load_dword v129, v115, s[26:27]
	s_add_u32 s26, s26, 0x1800
	s_addc_u32 s27, s27, 0
	global_load_dword v130, v115, s[26:27]
	s_add_u32 s26, s26, 0x1800
	s_addc_u32 s27, s27, 0
	global_load_dword v131, v115, s[26:27]
	s_add_u32 s26, s26, 0x1800
	s_addc_u32 s27, s27, 0
	global_load_dword v132, v115, s[26:27]
	s_add_u32 s26, s26, 0x1800
	s_addc_u32 s27, s27, 0
	global_load_dword v133, v115, s[26:27]
	s_add_u32 s26, s26, 0x1800
	s_addc_u32 s27, s27, 0
	global_load_dword v134, v115, s[26:27]
	s_add_u32 s26, s26, 0x1800
	s_addc_u32 s27, s27, 0
	global_load_dword v135, v115, s[26:27]
	s_add_u32 s26, s26, 0x1800
	s_addc_u32 s27, s27, 0
	global_load_dword v136, v115, s[26:27]
	s_add_u32 s26, s26, 0x1800
	s_addc_u32 s27, s27, 0
	global_load_dword v137, v115, s[26:27]
	s_add_u32 s26, s26, 0x1800
	s_addc_u32 s27, s27, 0
	global_load_dword v138, v115, s[26:27]
	s_add_u32 s26, s26, 0x1800
	s_addc_u32 s27, s27, 0
	global_load_dword v139, v115, s[26:27]
	s_add_u32 s26, s26, 0x1800
	s_addc_u32 s27, s27, 0
	global_load_dword v140, v115, s[26:27]
	s_add_u32 s26, s26, 0x1800
	s_addc_u32 s27, s27, 0
	global_load_dword v141, v115, s[26:27]
	s_add_u32 s26, s26, 0x1800
	s_addc_u32 s27, s27, 0
	global_load_dword v142, v115, s[26:27]
	s_add_u32 s26, s26, 0x1800
	s_addc_u32 s27, s27, 0
	global_load_dword v143, v115, s[26:27]
	s_add_u32 s26, s26, 0x1800
	s_addc_u32 s27, s27, 0
	global_load_dword v144, v115, s[26:27]
	s_add_u32 s26, s26, 0x1800
	s_addc_u32 s27, s27, 0
	global_load_dword v145, v115, s[26:27]
	s_add_u32 s26, s26, 0x1800
	s_addc_u32 s27, s27, 0
	global_load_dword v146, v115, s[26:27]
	s_add_u32 s26, s26, 0x1800
	s_addc_u32 s27, s27, 0
	global_load_dword v147, v115, s[26:27]
	s_add_u32 s26, s26, 0x1800
	s_addc_u32 s27, s27, 0
	global_load_dword v148, v115, s[26:27]
	s_add_u32 s26, s26, 0x1800
	s_addc_u32 s27, s27, 0
	global_load_dword v149, v115, s[26:27]
	s_add_u32 s26, s26, 0x1800
	s_addc_u32 s27, s27, 0
	global_load_dword v150, v115, s[26:27]
	s_add_u32 s26, s26, 0x1800
	s_addc_u32 s27, s27, 0
	global_load_dword v151, v115, s[26:27]
	s_add_u32 s26, s26, 0x1800
	s_addc_u32 s27, s27, 0
	global_load_dword v152, v115, s[26:27]
	s_add_u32 s26, s26, 0x1800
	s_addc_u32 s27, s27, 0
	global_load_dword v153, v115, s[26:27]
	s_add_u32 s26, s26, 0x1800
	s_addc_u32 s27, s27, 0
	global_load_dword v154, v115, s[26:27]
	s_add_u32 s26, s26, 0x1800
	s_addc_u32 s27, s27, 0
	global_load_dword v155, v115, s[26:27]
	s_add_u32 s26, s26, 0x1800
	s_addc_u32 s27, s27, 0
	global_load_dword v156, v115, s[26:27]
	s_add_u32 s26, s26, 0x1800
	s_addc_u32 s27, s27, 0
	global_load_dword v157, v115, s[26:27]
	s_add_u32 s26, s26, 0x1800
	s_addc_u32 s27, s27, 0
	global_load_dword v158, v115, s[26:27]
	s_add_u32 s26, s26, 0x1800
	s_addc_u32 s27, s27, 0
	global_load_dword v159, v115, s[26:27]
	s_waitcnt vmcnt(56)
; __device__ __forceinline__ void kraw_items(const Args& a, int gw, int NGW, int lane) {
;     ...
;             for (int ci = 0; ci < 12; ++ci) { const int c = c0 + 12 * cb + ci;
;                 float acc = 0.f;
; #pragma unroll
;                 for (int jj = 0; jj < 64; ++jj) acc += h[jj] * __builtin_bit_cast(float, __builtin_amdgcn_readlane(__builtin_bit_cast(int, wv[ci]), jj));
;                 const int cm = c % 768;
;                 const float delta = fabsf(-3.0701134573253945f + (float)cm * ((-15.350567286626973f + 3.0701134573253945f) / 767.0f));
;                 KR[(size_t)c * (LP + LS) + p] = acc * __expf(-tt * delta); }
	v_mfma_f32_32x32x2_f32 v[96:111], v64, v0, 0
	v_mfma_f32_32x32x2_f32 v[96:111], v65, v1, v[96:111]
	v_mfma_f32_32x32x2_f32 v[96:111], v66, v2, v[96:111]
	v_mfma_f32_32x32x2_f32 v[96:111], v67, v3, v[96:111]
	v_mfma_f32_32x32x2_f32 v[96:111], v68, v4, v[96:111]
	v_mfma_f32_32x32x2_f32 v[96:111], v69, v5, v[96:111]
	v_mfma_f32_32x32x2_f32 v[96:111], v70, v6, v[96:111]
	v_mfma_f32_32x32x2_f32 v[96:111], v71, v7, v[96:111]
	v_mfma_f32_32x32x2_f32 v[96:111], v72, v8, v[96:111]
	v_mfma_f32_32x32x2_f32 v[96:111], v73, v9, v[96:111]
	v_mfma_f32_32x32x2_f32 v[96:111], v74, v10, v[96:111]
	v_mfma_f32_32x32x2_f32 v[96:111], v75, v11, v[96:111]
	v_mfma_f32_32x32x2_f32 v[96:111], v76, v12, v[96:111]
	v_mfma_f32_32x32x2_f32 v[96:111], v77, v13, v[96:111]
	v_mfma_f32_32x32x2_f32 v[96:111], v78, v14, v[96:111]
	v_mfma_f32_32x32x2_f32 v[96:111], v79, v15, v[96:111]
	v_mfma_f32_32x32x2_f32 v[96:111], v80, v16, v[96:111]
	v_mfma_f32_32x32x2_f32 v[96:111], v81, v17, v[96:111]
	v_mfma_f32_32x32x2_f32 v[96:111], v82, v18, v[96:111]
	v_mfma_f32_32x32x2_f32 v[96:111], v83, v19, v[96:111]
	v_mfma_f32_32x32x2_f32 v[96:111], v84, v20, v[96:111]
	v_mfma_f32_32x32x2_f32 v[96:111], v85, v21, v[96:111]
	v_mfma_f32_32x32x2_f32 v[96:111], v86, v22, v[96:111]
	v_mfma_f32_32x32x2_f32 v[96:111], v87, v23, v[96:111]
	v_mfma_f32_32x32x2_f32 v[96:111], v88, v24, v[96:111]
	v_mfma_f32_32x32x2_f32 v[96:111], v89, v25, v[96:111]
	v_mfma_f32_32x32x2_f32 v[96:111], v90, v26, v[96:111]
	v_mfma_f32_32x32x2_f32 v[96:111], v91, v27, v[96:111]
	v_mfma_f32_32x32x2_f32 v[96:111], v92, v28, v[96:111]
	v_mfma_f32_32x32x2_f32 v[96:111], v93, v29, v[96:111]
	v_mfma_f32_32x32x2_f32 v[96:111], v94, v30, v[96:111]
	v_mfma_f32_32x32x2_f32 v[96:111], v95, v31, v[96:111]
	s_add_i32 s30, s29, 0
	v_add_u32_e32 v119, s30, v118
	v_cvt_f32_u32_e32 v119, v119
	v_fmamk_f32 v119, v119, 0xbc83298c, v120
	v_mul_f32_e64 v119, v117, |v119|
	v_mul_f32_e32 v119, 0x3fb8aa3b, v119
	v_exp_f32_e32 v160, v119
	s_add_i32 s30, s29, 1
	v_add_u32_e32 v119, s30, v118
	v_cvt_f32_u32_e32 v119, v119
	v_fmamk_f32 v119, v119, 0xbc83298c, v120
	v_mul_f32_e64 v119, v117, |v119|
	v_mul_f32_e32 v119, 0x3fb8aa3b, v119
	v_exp_f32_e32 v161, v119
	s_add_i32 s30, s29, 2
	v_add_u32_e32 v119, s30, v118
	v_cvt_f32_u32_e32 v119, v119
	v_fmamk_f32 v119, v119, 0xbc83298c, v120
	v_mul_f32_e64 v119, v117, |v119|
	v_mul_f32_e32 v119, 0x3fb8aa3b, v119
	v_exp_f32_e32 v162, v119
	s_add_i32 s30, s29, 3
	v_add_u32_e32 v119, s30, v118
	v_cvt_f32_u32_e32 v119, v119
	v_fmamk_f32 v119, v119, 0xbc83298c, v120
	v_mul_f32_e64 v119, v117, |v119|
	v_mul_f32_e32 v119, 0x3fb8aa3b, v119
	v_exp_f32_e32 v163, v119
	s_add_i32 s30, s29, 8
	v_add_u32_e32 v119, s30, v118
	v_cvt_f32_u32_e32 v119, v119
	v_fmamk_f32 v119, v119, 0xbc83298c, v120
	v_mul_f32_e64 v119, v117, |v119|
	v_mul_f32_e32 v119, 0x3fb8aa3b, v119
	v_exp_f32_e32 v164, v119
	s_add_i32 s30, s29, 9
	v_add_u32_e32 v119, s30, v118
	v_cvt_f32_u32_e32 v119, v119
	v_fmamk_f32 v119, v119, 0xbc83298c, v120
	v_mul_f32_e64 v119, v117, |v119|
	v_mul_f32_e32 v119, 0x3fb8aa3b, v119
	v_exp_f32_e32 v165, v119
	s_add_i32 s30, s29, 10
	v_add_u32_e32 v119, s30, v118
	v_cvt_f32_u32_e32 v119, v119
	v_fmamk_f32 v119, v119, 0xbc83298c, v120
	v_mul_f32_e64 v119, v117, |v119|
	v_mul_f32_e32 v119, 0x3fb8aa3b, v119
	v_exp_f32_e32 v166, v119
	s_add_i32 s30, s29, 11
	v_add_u32_e32 v119, s30, v118
	v_cvt_f32_u32_e32 v119, v119
	v_fmamk_f32 v119, v119, 0xbc83298c, v120
	v_mul_f32_e64 v119, v117, |v119|
	v_mul_f32_e32 v119, 0x3fb8aa3b, v119
	v_exp_f32_e32 v167, v119
	s_add_i32 s30, s29, 16
	v_add_u32_e32 v119, s30, v118
	v_cvt_f32_u32_e32 v119, v119
	v_fmamk_f32 v119, v119, 0xbc83298c, v120
	v_mul_f32_e64 v119, v117, |v119|
	v_mul_f32_e32 v119, 0x3fb8aa3b, v119
	v_exp_f32_e32 v168, v119
	s_add_i32 s30, s29, 17
	v_add_u32_e32 v119, s30, v118
	v_cvt_f32_u32_e32 v119, v119
	v_fmamk_f32 v119, v119, 0xbc83298c, v120
	v_mul_f32_e64 v119, v117, |v119|
	v_mul_f32_e32 v119, 0x3fb8aa3b, v119
	v_exp_f32_e32 v169, v119
	s_add_i32 s30, s29, 18
	v_add_u32_e32 v119, s30, v118
	v_cvt_f32_u32_e32 v119, v119
	v_fmamk_f32 v119, v119, 0xbc83298c, v120
	v_mul_f32_e64 v119, v117, |v119|
	v_mul_f32_e32 v119, 0x3fb8aa3b, v119
	v_exp_f32_e32 v170, v119
	s_add_i32 s30, s29, 19
	v_add_u32_e32 v119, s30, v118
	v_cvt_f32_u32_e32 v119, v119
	v_fmamk_f32 v119, v119, 0xbc83298c, v120
	v_mul_f32_e64 v119, v117, |v119|
	v_mul_f32_e32 v119, 0x3fb8aa3b, v119
	v_exp_f32_e32 v171, v119
	s_add_i32 s30, s29, 24
	v_add_u32_e32 v119, s30, v118
	v_cvt_f32_u32_e32 v119, v119
	v_fmamk_f32 v119, v119, 0xbc83298c, v120
	v_mul_f32_e64 v119, v117, |v119|
	v_mul_f32_e32 v119, 0x3fb8aa3b, v119
	v_exp_f32_e32 v172, v119
	s_add_i32 s30, s29, 25
	v_add_u32_e32 v119, s30, v118
	v_cvt_f32_u32_e32 v119, v119
	v_fmamk_f32 v119, v119, 0xbc83298c, v120
	v_mul_f32_e64 v119, v117, |v119|
	v_mul_f32_e32 v119, 0x3fb8aa3b, v119
	v_exp_f32_e32 v173, v119
	s_add_i32 s30, s29, 26
	v_add_u32_e32 v119, s30, v118
	v_cvt_f32_u32_e32 v119, v119
	v_fmamk_f32 v119, v119, 0xbc83298c, v120
	v_mul_f32_e64 v119, v117, |v119|
	v_mul_f32_e32 v119, 0x3fb8aa3b, v119
	v_exp_f32_e32 v174, v119
	s_add_i32 s30, s29, 27
	v_add_u32_e32 v119, s30, v118
	v_cvt_f32_u32_e32 v119, v119
	v_fmamk_f32 v119, v119, 0xbc83298c, v120
	v_mul_f32_e64 v119, v117, |v119|
	v_mul_f32_e32 v119, 0x3fb8aa3b, v119
	v_exp_f32_e32 v175, v119
	s_nop 7
	v_mul_f32_e32 v176, v96, v160
	s_mov_b64 s[36:37], s[34:35]
	global_store_dword v115, v176, s[36:37] nt
	v_mul_f32_e32 v177, v97, v161
	s_add_u32 s36, s34, 0xc000
	s_addc_u32 s37, s35, 0
	global_store_dword v115, v177, s[36:37] nt
	v_mul_f32_e32 v178, v98, v162
	s_add_u32 s36, s34, 0x18000
; __device__ __forceinline__ void kraw_items(const Args& a, int gw, int NGW, int lane) {
;     ...
;         const int grp = p >= LP, tpos = p - grp * LP, L = grp ? LS : LP;
;         const float tt = (float)tpos * (1.0f / (float)(L - 1));
; #pragma unroll 1
;         for (int cb = 0; cb < 4; ++cb) {
;             const float* wr = a.in[I_FWOUT] + lane * 1536 + c0 + 12 * cb;
;             const f32x4 w0 = *(const f32x4*)(wr), w1 = *(const f32x4*)(wr + 4), w2 = *(const f32x4*)(wr + 8);
;             float wv[12] = {w0.x, w0.y, w0.z, w0.w, w1.x, w1.y, w1.z, w1.w, w2.x, w2.y, w2.z, w2.w};
;     ...
;                 KR[(size_t)c * (LP + LS) + p] = acc * __expf(-tt * delta); }
	s_addc_u32 s37, s35, 0
	global_store_dword v115, v178, s[36:37] nt
	v_mul_f32_e32 v179, v99, v163
	s_add_u32 s36, s34, 0x24000
	s_addc_u32 s37, s35, 0
	global_store_dword v115, v179, s[36:37] nt
	v_mul_f32_e32 v180, v100, v164
	s_add_u32 s36, s34, 0x60000
	s_addc_u32 s37, s35, 0
	global_store_dword v115, v180, s[36:37] nt
	v_mul_f32_e32 v181, v101, v165
	s_add_u32 s36, s34, 0x6c000
	s_addc_u32 s37, s35, 0
	global_store_dword v115, v181, s[36:37] nt
	v_mul_f32_e32 v182, v102, v166
	s_add_u32 s36, s34, 0x78000
	s_addc_u32 s37, s35, 0
	global_store_dword v115, v182, s[36:37] nt
	v_mul_f32_e32 v183, v103, v167
	s_add_u32 s36, s34, 0x84000
	s_addc_u32 s37, s35, 0
	global_store_dword v115, v183, s[36:37] nt
	v_mul_f32_e32 v184, v104, v168
	s_add_u32 s36, s34, 0xc0000
	s_addc_u32 s37, s35, 0
	global_store_dword v115, v184, s[36:37] nt
	v_mul_f32_e32 v185, v105, v169
	s_add_u32 s36, s34, 0xcc000
	s_addc_u32 s37, s35, 0
	global_store_dword v115, v185, s[36:37] nt
	v_mul_f32_e32 v186, v106, v170
	s_add_u32 s36, s34, 0xd8000
	s_addc_u32 s37, s35, 0
	global_store_dword v115, v186, s[36:37] nt
	v_mul_f32_e32 v187, v107, v171
	s_add_u32 s36, s34, 0xe4000
	s_addc_u32 s37, s35, 0
	global_store_dword v115, v187, s[36:37] nt
	v_mul_f32_e32 v188, v108, v172
	s_add_u32 s36, s34, 0x120000
	s_addc_u32 s37, s35, 0
	global_store_dword v115, v188, s[36:37] nt
	v_mul_f32_e32 v189, v109, v173
	s_add_u32 s36, s34, 0x12c000
	s_addc_u32 s37, s35, 0
	global_store_dword v115, v189, s[36:37] nt
	v_mul_f32_e32 v190, v110, v174
	s_add_u32 s36, s34, 0x138000
	s_addc_u32 s37, s35, 0
	global_store_dword v115, v190, s[36:37] nt
	v_mul_f32_e32 v191, v111, v175
	s_add_u32 s36, s34, 0x144000
	s_addc_u32 s37, s35, 0
	global_store_dword v115, v191, s[36:37] nt
	s_add_i32 s28, s21, 0
	s_sub_i32 s29, s28, 0x300
	s_cmp_ge_u32 s28, 0x300
	s_cselect_b32 s29, s29, s28
	s_mul_i32 s30, s28, 0xc000
	s_lshl_b32 s35, s20, 2
	s_add_u32 s30, s30, s35
	s_add_u32 s34, s14, s30
	s_addc_u32 s35, s15, 0
	s_mov_b32 s22, 0xb9000400
	s_cmp_ge_u32 s20, 0x2000
	s_cselect_b32 s22, 0xb9800801, s22
	s_and_b32 s30, s20, 0x1fff
	v_add_u32_e32 v119, s30, v112
	v_cvt_f32_u32_e32 v119, v119
	v_mul_f32_e32 v117, s22, v119
	s_add_i32 s30, s21, 32
	s_lshl_b32 s30, s30, 2
	s_add_u32 s26, s6, s30
	s_addc_u32 s27, s7, 0
	global_load_dword v64, v115, s[26:27]
	s_add_u32 s26, s26, 0x1800
	s_addc_u32 s27, s27, 0
	global_load_dword v65, v115, s[26:27]
	s_add_u32 s26, s26, 0x1800
	s_addc_u32 s27, s27, 0
	global_load_dword v66, v115, s[26:27]
	s_add_u32 s26, s26, 0x1800
	s_addc_u32 s27, s27, 0
	global_load_dword v67, v115, s[26:27]
	s_add_u32 s26, s26, 0x1800
	s_addc_u32 s27, s27, 0
	global_load_dword v68, v115, s[26:27]
	s_add_u32 s26, s26, 0x1800
	s_addc_u32 s27, s27, 0
	global_load_dword v69, v115, s[26:27]
	s_add_u32 s26, s26, 0x1800
	s_addc_u32 s27, s27, 0
	global_load_dword v70, v115, s[26:27]
	s_add_u32 s26, s26, 0x1800
	s_addc_u32 s27, s27, 0
	global_load_dword v71, v115, s[26:27]
	s_add_u32 s26, s26, 0x1800
	s_addc_u32 s27, s27, 0
	global_load_dword v72, v115, s[26:27]
	s_add_u32 s26, s26, 0x1800
	s_addc_u32 s27, s27, 0
	global_load_dword v73, v115, s[26:27]
	s_add_u32 s26, s26, 0x1800
	s_addc_u32 s27, s27, 0
	global_load_dword v74, v115, s[26:27]
	s_add_u32 s26, s26, 0x1800
	s_addc_u32 s27, s27, 0
	global_load_dword v75, v115, s[26:27]
	s_add_u32 s26, s26, 0x1800
	s_addc_u32 s27, s27, 0
	global_load_dword v76, v115, s[26:27]
	s_add_u32 s26, s26, 0x1800
	s_addc_u32 s27, s27, 0
	global_load_dword v77, v115, s[26:27]
	s_add_u32 s26, s26, 0x1800
	s_addc_u32 s27, s27, 0
	global_load_dword v78, v115, s[26:27]
	s_add_u32 s26, s26, 0x1800
	s_addc_u32 s27, s27, 0
	global_load_dword v79, v115, s[26:27]
	s_add_u32 s26, s26, 0x1800
	s_addc_u32 s27, s27, 0
	global_load_dword v80, v115, s[26:27]
	s_add_u32 s26, s26, 0x1800
	s_addc_u32 s27, s27, 0
	global_load_dword v81, v115, s[26:27]
	s_add_u32 s26, s26, 0x1800
	s_addc_u32 s27, s27, 0
	global_load_dword v82, v115, s[26:27]
	s_add_u32 s26, s26, 0x1800
	s_addc_u32 s27, s27, 0
	global_load_dword v83, v115, s[26:27]
	s_add_u32 s26, s26, 0x1800
	s_addc_u32 s27, s27, 0
	global_load_dword v84, v115, s[26:27]
	s_add_u32 s26, s26, 0x1800
	s_addc_u32 s27, s27, 0
	global_load_dword v85, v115, s[26:27]
	s_add_u32 s26, s26, 0x1800
	s_addc_u32 s27, s27, 0
	global_load_dword v86, v115, s[26:27]
	s_add_u32 s26, s26, 0x1800
	s_addc_u32 s27, s27, 0
	global_load_dword v87, v115, s[26:27]
	s_add_u32 s26, s26, 0x1800
	s_addc_u32 s27, s27, 0
	global_load_dword v88, v115, s[26:27]
	s_add_u32 s26, s26, 0x1800
	s_addc_u32 s27, s27, 0
	global_load_dword v89, v115, s[26:27]
	s_add_u32 s26, s26, 0x1800
	s_addc_u32 s27, s27, 0
	global_load_dword v90, v115, s[26:27]
	s_add_u32 s26, s26, 0x1800
	s_addc_u32 s27, s27, 0
	global_load_dword v91, v115, s[26:27]
	s_add_u32 s26, s26, 0x1800
	s_addc_u32 s27, s27, 0
	global_load_dword v92, v115, s[26:27]
	s_add_u32 s26, s26, 0x1800
	s_addc_u32 s27, s27, 0
	global_load_dword v93, v115, s[26:27]
	s_add_u32 s26, s26, 0x1800
	s_addc_u32 s27, s27, 0
	global_load_dword v94, v115, s[26:27]
	s_add_u32 s26, s26, 0x1800
	s_addc_u32 s27, s27, 0
	global_load_dword v95, v115, s[26:27]
	s_waitcnt vmcnt(48)
; __device__ __forceinline__ void kraw_items(const Args& a, int gw, int NGW, int lane) {
;     ...
;             for (int ci = 0; ci < 12; ++ci) { const int c = c0 + 12 * cb + ci;
;                 float acc = 0.f;
; #pragma unroll
;                 for (int jj = 0; jj < 64; ++jj) acc += h[jj] * __builtin_bit_cast(float, __builtin_amdgcn_readlane(__builtin_bit_cast(int, wv[ci]), jj));
;                 const int cm = c % 768;
;                 const float delta = fabsf(-3.0701134573253945f + (float)cm * ((-15.350567286626973f + 3.0701134573253945f) / 767.0f));
;                 KR[(size_t)c * (LP + LS) + p] = acc * __expf(-tt * delta); }
	v_mfma_f32_32x32x2_f32 v[96:111], v128, v32, 0
	v_mfma_f32_32x32x2_f32 v[96:111], v129, v33, v[96:111]
	v_mfma_f32_32x32x2_f32 v[96:111], v130, v34, v[96:111]
	v_mfma_f32_32x32x2_f32 v[96:111], v131, v35, v[96:111]
	v_mfma_f32_32x32x2_f32 v[96:111], v132, v36, v[96:111]
	v_mfma_f32_32x32x2_f32 v[96:111], v133, v37, v[96:111]
	v_mfma_f32_32x32x2_f32 v[96:111], v134, v38, v[96:111]
	v_mfma_f32_32x32x2_f32 v[96:111], v135, v39, v[96:111]
	v_mfma_f32_32x32x2_f32 v[96:111], v136, v40, v[96:111]
	v_mfma_f32_32x32x2_f32 v[96:111], v137, v41, v[96:111]
	v_mfma_f32_32x32x2_f32 v[96:111], v138, v42, v[96:111]
	v_mfma_f32_32x32x2_f32 v[96:111], v139, v43, v[96:111]
	v_mfma_f32_32x32x2_f32 v[96:111], v140, v44, v[96:111]
	v_mfma_f32_32x32x2_f32 v[96:111], v141, v45, v[96:111]
	v_mfma_f32_32x32x2_f32 v[96:111], v142, v46, v[96:111]
	v_mfma_f32_32x32x2_f32 v[96:111], v143, v47, v[96:111]
	v_mfma_f32_32x32x2_f32 v[96:111], v144, v48, v[96:111]
	v_mfma_f32_32x32x2_f32 v[96:111], v145, v49, v[96:111]
	v_mfma_f32_32x32x2_f32 v[96:111], v146, v50, v[96:111]
	v_mfma_f32_32x32x2_f32 v[96:111], v147, v51, v[96:111]
	v_mfma_f32_32x32x2_f32 v[96:111], v148, v52, v[96:111]
	v_mfma_f32_32x32x2_f32 v[96:111], v149, v53, v[96:111]
	v_mfma_f32_32x32x2_f32 v[96:111], v150, v54, v[96:111]
	v_mfma_f32_32x32x2_f32 v[96:111], v151, v55, v[96:111]
	v_mfma_f32_32x32x2_f32 v[96:111], v152, v56, v[96:111]
	v_mfma_f32_32x32x2_f32 v[96:111], v153, v57, v[96:111]
	v_mfma_f32_32x32x2_f32 v[96:111], v154, v58, v[96:111]
	v_mfma_f32_32x32x2_f32 v[96:111], v155, v59, v[96:111]
	v_mfma_f32_32x32x2_f32 v[96:111], v156, v60, v[96:111]
	v_mfma_f32_32x32x2_f32 v[96:111], v157, v61, v[96:111]
	v_mfma_f32_32x32x2_f32 v[96:111], v158, v62, v[96:111]
	v_mfma_f32_32x32x2_f32 v[96:111], v159, v63, v[96:111]
	s_add_i32 s30, s29, 0
	v_add_u32_e32 v119, s30, v118
	v_cvt_f32_u32_e32 v119, v119
	v_fmamk_f32 v119, v119, 0xbc83298c, v120
	v_mul_f32_e64 v119, v117, |v119|
	v_mul_f32_e32 v119, 0x3fb8aa3b, v119
	v_exp_f32_e32 v160, v119
	s_add_i32 s30, s29, 1
	v_add_u32_e32 v119, s30, v118
	v_cvt_f32_u32_e32 v119, v119
	v_fmamk_f32 v119, v119, 0xbc83298c, v120
	v_mul_f32_e64 v119, v117, |v119|
	v_mul_f32_e32 v119, 0x3fb8aa3b, v119
	v_exp_f32_e32 v161, v119
	s_add_i32 s30, s29, 2
	v_add_u32_e32 v119, s30, v118
	v_cvt_f32_u32_e32 v119, v119
	v_fmamk_f32 v119, v119, 0xbc83298c, v120
	v_mul_f32_e64 v119, v117, |v119|
	v_mul_f32_e32 v119, 0x3fb8aa3b, v119
	v_exp_f32_e32 v162, v119
	s_add_i32 s30, s29, 3
	v_add_u32_e32 v119, s30, v118
	v_cvt_f32_u32_e32 v119, v119
	v_fmamk_f32 v119, v119, 0xbc83298c, v120
	v_mul_f32_e64 v119, v117, |v119|
	v_mul_f32_e32 v119, 0x3fb8aa3b, v119
	v_exp_f32_e32 v163, v119
	s_add_i32 s30, s29, 8
	v_add_u32_e32 v119, s30, v118
	v_cvt_f32_u32_e32 v119, v119
	v_fmamk_f32 v119, v119, 0xbc83298c, v120
	v_mul_f32_e64 v119, v117, |v119|
	v_mul_f32_e32 v119, 0x3fb8aa3b, v119
	v_exp_f32_e32 v164, v119
	s_add_i32 s30, s29, 9
	v_add_u32_e32 v119, s30, v118
	v_cvt_f32_u32_e32 v119, v119
	v_fmamk_f32 v119, v119, 0xbc83298c, v120
	v_mul_f32_e64 v119, v117, |v119|
	v_mul_f32_e32 v119, 0x3fb8aa3b, v119
	v_exp_f32_e32 v165, v119
	s_add_i32 s30, s29, 10
	v_add_u32_e32 v119, s30, v118
	v_cvt_f32_u32_e32 v119, v119
	v_fmamk_f32 v119, v119, 0xbc83298c, v120
	v_mul_f32_e64 v119, v117, |v119|
	v_mul_f32_e32 v119, 0x3fb8aa3b, v119
	v_exp_f32_e32 v166, v119
	s_add_i32 s30, s29, 11
	v_add_u32_e32 v119, s30, v118
	v_cvt_f32_u32_e32 v119, v119
	v_fmamk_f32 v119, v119, 0xbc83298c, v120
	v_mul_f32_e64 v119, v117, |v119|
	v_mul_f32_e32 v119, 0x3fb8aa3b, v119
	v_exp_f32_e32 v167, v119
	s_add_i32 s30, s29, 16
	v_add_u32_e32 v119, s30, v118
	v_cvt_f32_u32_e32 v119, v119
	v_fmamk_f32 v119, v119, 0xbc83298c, v120
	v_mul_f32_e64 v119, v117, |v119|
	v_mul_f32_e32 v119, 0x3fb8aa3b, v119
	v_exp_f32_e32 v168, v119
	s_add_i32 s30, s29, 17
	v_add_u32_e32 v119, s30, v118
	v_cvt_f32_u32_e32 v119, v119
	v_fmamk_f32 v119, v119, 0xbc83298c, v120
	v_mul_f32_e64 v119, v117, |v119|
	v_mul_f32_e32 v119, 0x3fb8aa3b, v119
	v_exp_f32_e32 v169, v119
	s_add_i32 s30, s29, 18
	v_add_u32_e32 v119, s30, v118
	v_cvt_f32_u32_e32 v119, v119
	v_fmamk_f32 v119, v119, 0xbc83298c, v120
	v_mul_f32_e64 v119, v117, |v119|
	v_mul_f32_e32 v119, 0x3fb8aa3b, v119
	v_exp_f32_e32 v170, v119
	s_add_i32 s30, s29, 19
	v_add_u32_e32 v119, s30, v118
	v_cvt_f32_u32_e32 v119, v119
	v_fmamk_f32 v119, v119, 0xbc83298c, v120
	v_mul_f32_e64 v119, v117, |v119|
	v_mul_f32_e32 v119, 0x3fb8aa3b, v119
	v_exp_f32_e32 v171, v119
	s_add_i32 s30, s29, 24
	v_add_u32_e32 v119, s30, v118
	v_cvt_f32_u32_e32 v119, v119
	v_fmamk_f32 v119, v119, 0xbc83298c, v120
	v_mul_f32_e64 v119, v117, |v119|
	v_mul_f32_e32 v119, 0x3fb8aa3b, v119
	v_exp_f32_e32 v172, v119
	s_add_i32 s30, s29, 25
	v_add_u32_e32 v119, s30, v118
	v_cvt_f32_u32_e32 v119, v119
	v_fmamk_f32 v119, v119, 0xbc83298c, v120
	v_mul_f32_e64 v119, v117, |v119|
	v_mul_f32_e32 v119, 0x3fb8aa3b, v119
	v_exp_f32_e32 v173, v119
	s_add_i32 s30, s29, 26
	v_add_u32_e32 v119, s30, v118
	v_cvt_f32_u32_e32 v119, v119
	v_fmamk_f32 v119, v119, 0xbc83298c, v120
	v_mul_f32_e64 v119, v117, |v119|
	v_mul_f32_e32 v119, 0x3fb8aa3b, v119
	v_exp_f32_e32 v174, v119
	s_add_i32 s30, s29, 27
	v_add_u32_e32 v119, s30, v118
	v_cvt_f32_u32_e32 v119, v119
	v_fmamk_f32 v119, v119, 0xbc83298c, v120
	v_mul_f32_e64 v119, v117, |v119|
	v_mul_f32_e32 v119, 0x3fb8aa3b, v119
	v_exp_f32_e32 v175, v119
	s_nop 7
	v_mul_f32_e32 v176, v96, v160
	s_mov_b64 s[36:37], s[34:35]
	global_store_dword v115, v176, s[36:37] nt
	v_mul_f32_e32 v177, v97, v161
	s_add_u32 s36, s34, 0xc000
	s_addc_u32 s37, s35, 0
	global_store_dword v115, v177, s[36:37] nt
	v_mul_f32_e32 v178, v98, v162
; __device__ __forceinline__ void kraw_items(const Args& a, int gw, int NGW, int lane) {
;     ...
;         for (int cb = 0; cb < 4; ++cb) {
;             const float* wr = a.in[I_FWOUT] + lane * 1536 + c0 + 12 * cb;
;             const f32x4 w0 = *(const f32x4*)(wr), w1 = *(const f32x4*)(wr + 4), w2 = *(const f32x4*)(wr + 8);
;             float wv[12] = {w0.x, w0.y, w0.z, w0.w, w1.x, w1.y, w1.z, w1.w, w2.x, w2.y, w2.z, w2.w};
;     ...
;                 KR[(size_t)c * (LP + LS) + p] = acc * __expf(-tt * delta); }
	s_add_u32 s36, s34, 0x18000
	s_addc_u32 s37, s35, 0
	global_store_dword v115, v178, s[36:37] nt
	v_mul_f32_e32 v179, v99, v163
	s_add_u32 s36, s34, 0x24000
	s_addc_u32 s37, s35, 0
	global_store_dword v115, v179, s[36:37] nt
	v_mul_f32_e32 v180, v100, v164
	s_add_u32 s36, s34, 0x60000
	s_addc_u32 s37, s35, 0
	global_store_dword v115, v180, s[36:37] nt
	v_mul_f32_e32 v181, v101, v165
	s_add_u32 s36, s34, 0x6c000
	s_addc_u32 s37, s35, 0
	global_store_dword v115, v181, s[36:37] nt
	v_mul_f32_e32 v182, v102, v166
	s_add_u32 s36, s34, 0x78000
	s_addc_u32 s37, s35, 0
	global_store_dword v115, v182, s[36:37] nt
	v_mul_f32_e32 v183, v103, v167
	s_add_u32 s36, s34, 0x84000
	s_addc_u32 s37, s35, 0
	global_store_dword v115, v183, s[36:37] nt
	v_mul_f32_e32 v184, v104, v168
	s_add_u32 s36, s34, 0xc0000
	s_addc_u32 s37, s35, 0
	global_store_dword v115, v184, s[36:37] nt
	v_mul_f32_e32 v185, v105, v169
	s_add_u32 s36, s34, 0xcc000
	s_addc_u32 s37, s35, 0
	global_store_dword v115, v185, s[36:37] nt
	v_mul_f32_e32 v186, v106, v170
	s_add_u32 s36, s34, 0xd8000
	s_addc_u32 s37, s35, 0
	global_store_dword v115, v186, s[36:37] nt
	v_mul_f32_e32 v187, v107, v171
	s_add_u32 s36, s34, 0xe4000
	s_addc_u32 s37, s35, 0
	global_store_dword v115, v187, s[36:37] nt
	v_mul_f32_e32 v188, v108, v172
	s_add_u32 s36, s34, 0x120000
	s_addc_u32 s37, s35, 0
	global_store_dword v115, v188, s[36:37] nt
	v_mul_f32_e32 v189, v109, v173
	s_add_u32 s36, s34, 0x12c000
	s_addc_u32 s37, s35, 0
	global_store_dword v115, v189, s[36:37] nt
	v_mul_f32_e32 v190, v110, v174
	s_add_u32 s36, s34, 0x138000
	s_addc_u32 s37, s35, 0
	global_store_dword v115, v190, s[36:37] nt
	v_mul_f32_e32 v191, v111, v175
	s_add_u32 s36, s34, 0x144000
	s_addc_u32 s37, s35, 0
	global_store_dword v115, v191, s[36:37] nt
	s_add_i32 s28, s21, 32
	s_sub_i32 s29, s28, 0x300
	s_cmp_ge_u32 s28, 0x300
	s_cselect_b32 s29, s29, s28
	s_mul_i32 s30, s28, 0xc000
	s_lshl_b32 s35, s20, 2
	s_add_u32 s30, s30, s35
	s_add_u32 s34, s14, s30
	s_addc_u32 s35, s15, 0
	s_add_i32 s30, s21, 64
	s_lshl_b32 s30, s30, 2
	s_add_u32 s26, s6, s30
	s_addc_u32 s27, s7, 0
	global_load_dword v128, v115, s[26:27]
	s_add_u32 s26, s26, 0x1800
	s_addc_u32 s27, s27, 0
	global_load_dword v129, v115, s[26:27]
	s_add_u32 s26, s26, 0x1800
	s_addc_u32 s27, s27, 0
	global_load_dword v130, v115, s[26:27]
	s_add_u32 s26, s26, 0x1800
	s_addc_u32 s27, s27, 0
	global_load_dword v131, v115, s[26:27]
	s_add_u32 s26, s26, 0x1800
	s_addc_u32 s27, s27, 0
	global_load_dword v132, v115, s[26:27]
	s_add_u32 s26, s26, 0x1800
	s_addc_u32 s27, s27, 0
	global_load_dword v133, v115, s[26:27]
	s_add_u32 s26, s26, 0x1800
	s_addc_u32 s27, s27, 0
	global_load_dword v134, v115, s[26:27]
	s_add_u32 s26, s26, 0x1800
	s_addc_u32 s27, s27, 0
	global_load_dword v135, v115, s[26:27]
	s_add_u32 s26, s26, 0x1800
	s_addc_u32 s27, s27, 0
	global_load_dword v136, v115, s[26:27]
	s_add_u32 s26, s26, 0x1800
	s_addc_u32 s27, s27, 0
	global_load_dword v137, v115, s[26:27]
	s_add_u32 s26, s26, 0x1800
	s_addc_u32 s27, s27, 0
	global_load_dword v138, v115, s[26:27]
	s_add_u32 s26, s26, 0x1800
	s_addc_u32 s27, s27, 0
	global_load_dword v139, v115, s[26:27]
	s_add_u32 s26, s26, 0x1800
	s_addc_u32 s27, s27, 0
	global_load_dword v140, v115, s[26:27]
	s_add_u32 s26, s26, 0x1800
	s_addc_u32 s27, s27, 0
	global_load_dword v141, v115, s[26:27]
	s_add_u32 s26, s26, 0x1800
	s_addc_u32 s27, s27, 0
	global_load_dword v142, v115, s[26:27]
	s_add_u32 s26, s26, 0x1800
	s_addc_u32 s27, s27, 0
	global_load_dword v143, v115, s[26:27]
	s_add_u32 s26, s26, 0x1800
	s_addc_u32 s27, s27, 0
	global_load_dword v144, v115, s[26:27]
	s_add_u32 s26, s26, 0x1800
	s_addc_u32 s27, s27, 0
	global_load_dword v145, v115, s[26:27]
	s_add_u32 s26, s26, 0x1800
	s_addc_u32 s27, s27, 0
	global_load_dword v146, v115, s[26:27]
	s_add_u32 s26, s26, 0x1800
	s_addc_u32 s27, s27, 0
	global_load_dword v147, v115, s[26:27]
	s_add_u32 s26, s26, 0x1800
	s_addc_u32 s27, s27, 0
	global_load_dword v148, v115, s[26:27]
	s_add_u32 s26, s26, 0x1800
	s_addc_u32 s27, s27, 0
	global_load_dword v149, v115, s[26:27]
	s_add_u32 s26, s26, 0x1800
	s_addc_u32 s27, s27, 0
	global_load_dword v150, v115, s[26:27]
	s_add_u32 s26, s26, 0x1800
	s_addc_u32 s27, s27, 0
	global_load_dword v151, v115, s[26:27]
	s_add_u32 s26, s26, 0x1800
	s_addc_u32 s27, s27, 0
	global_load_dword v152, v115, s[26:27]
	s_add_u32 s26, s26, 0x1800
	s_addc_u32 s27, s27, 0
	global_load_dword v153, v115, s[26:27]
	s_add_u32 s26, s26, 0x1800
	s_addc_u32 s27, s27, 0
	global_load_dword v154, v115, s[26:27]
	s_add_u32 s26, s26, 0x1800
	s_addc_u32 s27, s27, 0
	global_load_dword v155, v115, s[26:27]
	s_add_u32 s26, s26, 0x1800
	s_addc_u32 s27, s27, 0
	global_load_dword v156, v115, s[26:27]
	s_add_u32 s26, s26, 0x1800
	s_addc_u32 s27, s27, 0
	global_load_dword v157, v115, s[26:27]
	s_add_u32 s26, s26, 0x1800
	s_addc_u32 s27, s27, 0
	global_load_dword v158, v115, s[26:27]
	s_add_u32 s26, s26, 0x1800
	s_addc_u32 s27, s27, 0
	global_load_dword v159, v115, s[26:27]
	s_waitcnt vmcnt(48)
; __device__ __forceinline__ void kraw_items(const Args& a, int gw, int NGW, int lane) {
;     ...
;             for (int ci = 0; ci < 12; ++ci) { const int c = c0 + 12 * cb + ci;
;                 float acc = 0.f;
; #pragma unroll
;                 for (int jj = 0; jj < 64; ++jj) acc += h[jj] * __builtin_bit_cast(float, __builtin_amdgcn_readlane(__builtin_bit_cast(int, wv[ci]), jj));
;                 const int cm = c % 768;
;                 const float delta = fabsf(-3.0701134573253945f + (float)cm * ((-15.350567286626973f + 3.0701134573253945f) / 767.0f));
;                 KR[(size_t)c * (LP + LS) + p] = acc * __expf(-tt * delta); }
	v_mfma_f32_32x32x2_f32 v[96:111], v64, v32, 0
	v_mfma_f32_32x32x2_f32 v[96:111], v65, v33, v[96:111]
	v_mfma_f32_32x32x2_f32 v[96:111], v66, v34, v[96:111]
	v_mfma_f32_32x32x2_f32 v[96:111], v67, v35, v[96:111]
	v_mfma_f32_32x32x2_f32 v[96:111], v68, v36, v[96:111]
	v_mfma_f32_32x32x2_f32 v[96:111], v69, v37, v[96:111]
	v_mfma_f32_32x32x2_f32 v[96:111], v70, v38, v[96:111]
	v_mfma_f32_32x32x2_f32 v[96:111], v71, v39, v[96:111]
	v_mfma_f32_32x32x2_f32 v[96:111], v72, v40, v[96:111]
	v_mfma_f32_32x32x2_f32 v[96:111], v73, v41, v[96:111]
	v_mfma_f32_32x32x2_f32 v[96:111], v74, v42, v[96:111]
	v_mfma_f32_32x32x2_f32 v[96:111], v75, v43, v[96:111]
	v_mfma_f32_32x32x2_f32 v[96:111], v76, v44, v[96:111]
	v_mfma_f32_32x32x2_f32 v[96:111], v77, v45, v[96:111]
	v_mfma_f32_32x32x2_f32 v[96:111], v78, v46, v[96:111]
	v_mfma_f32_32x32x2_f32 v[96:111], v79, v47, v[96:111]
	v_mfma_f32_32x32x2_f32 v[96:111], v80, v48, v[96:111]
	v_mfma_f32_32x32x2_f32 v[96:111], v81, v49, v[96:111]
	v_mfma_f32_32x32x2_f32 v[96:111], v82, v50, v[96:111]
	v_mfma_f32_32x32x2_f32 v[96:111], v83, v51, v[96:111]
	v_mfma_f32_32x32x2_f32 v[96:111], v84, v52, v[96:111]
	v_mfma_f32_32x32x2_f32 v[96:111], v85, v53, v[96:111]
	v_mfma_f32_32x32x2_f32 v[96:111], v86, v54, v[96:111]
	v_mfma_f32_32x32x2_f32 v[96:111], v87, v55, v[96:111]
	v_mfma_f32_32x32x2_f32 v[96:111], v88, v56, v[96:111]
	v_mfma_f32_32x32x2_f32 v[96:111], v89, v57, v[96:111]
	v_mfma_f32_32x32x2_f32 v[96:111], v90, v58, v[96:111]
	v_mfma_f32_32x32x2_f32 v[96:111], v91, v59, v[96:111]
	v_mfma_f32_32x32x2_f32 v[96:111], v92, v60, v[96:111]
	v_mfma_f32_32x32x2_f32 v[96:111], v93, v61, v[96:111]
	v_mfma_f32_32x32x2_f32 v[96:111], v94, v62, v[96:111]
	v_mfma_f32_32x32x2_f32 v[96:111], v95, v63, v[96:111]
	s_add_i32 s30, s29, 0
	v_add_u32_e32 v119, s30, v118
	v_cvt_f32_u32_e32 v119, v119
	v_fmamk_f32 v119, v119, 0xbc83298c, v120
	v_mul_f32_e64 v119, v117, |v119|
	v_mul_f32_e32 v119, 0x3fb8aa3b, v119
	v_exp_f32_e32 v160, v119
	s_add_i32 s30, s29, 1
	v_add_u32_e32 v119, s30, v118
	v_cvt_f32_u32_e32 v119, v119
	v_fmamk_f32 v119, v119, 0xbc83298c, v120
	v_mul_f32_e64 v119, v117, |v119|
	v_mul_f32_e32 v119, 0x3fb8aa3b, v119
	v_exp_f32_e32 v161, v119
	s_add_i32 s30, s29, 2
	v_add_u32_e32 v119, s30, v118
	v_cvt_f32_u32_e32 v119, v119
	v_fmamk_f32 v119, v119, 0xbc83298c, v120
	v_mul_f32_e64 v119, v117, |v119|
	v_mul_f32_e32 v119, 0x3fb8aa3b, v119
	v_exp_f32_e32 v162, v119
	s_add_i32 s30, s29, 3
	v_add_u32_e32 v119, s30, v118
	v_cvt_f32_u32_e32 v119, v119
	v_fmamk_f32 v119, v119, 0xbc83298c, v120
	v_mul_f32_e64 v119, v117, |v119|
	v_mul_f32_e32 v119, 0x3fb8aa3b, v119
	v_exp_f32_e32 v163, v119
	s_add_i32 s30, s29, 8
	v_add_u32_e32 v119, s30, v118
	v_cvt_f32_u32_e32 v119, v119
	v_fmamk_f32 v119, v119, 0xbc83298c, v120
	v_mul_f32_e64 v119, v117, |v119|
	v_mul_f32_e32 v119, 0x3fb8aa3b, v119
	v_exp_f32_e32 v164, v119
	s_add_i32 s30, s29, 9
	v_add_u32_e32 v119, s30, v118
	v_cvt_f32_u32_e32 v119, v119
	v_fmamk_f32 v119, v119, 0xbc83298c, v120
	v_mul_f32_e64 v119, v117, |v119|
	v_mul_f32_e32 v119, 0x3fb8aa3b, v119
	v_exp_f32_e32 v165, v119
	s_add_i32 s30, s29, 10
	v_add_u32_e32 v119, s30, v118
	v_cvt_f32_u32_e32 v119, v119
	v_fmamk_f32 v119, v119, 0xbc83298c, v120
	v_mul_f32_e64 v119, v117, |v119|
	v_mul_f32_e32 v119, 0x3fb8aa3b, v119
	v_exp_f32_e32 v166, v119
	s_add_i32 s30, s29, 11
	v_add_u32_e32 v119, s30, v118
	v_cvt_f32_u32_e32 v119, v119
	v_fmamk_f32 v119, v119, 0xbc83298c, v120
	v_mul_f32_e64 v119, v117, |v119|
	v_mul_f32_e32 v119, 0x3fb8aa3b, v119
	v_exp_f32_e32 v167, v119
	s_add_i32 s30, s29, 16
	v_add_u32_e32 v119, s30, v118
	v_cvt_f32_u32_e32 v119, v119
	v_fmamk_f32 v119, v119, 0xbc83298c, v120
	v_mul_f32_e64 v119, v117, |v119|
	v_mul_f32_e32 v119, 0x3fb8aa3b, v119
	v_exp_f32_e32 v168, v119
	s_add_i32 s30, s29, 17
	v_add_u32_e32 v119, s30, v118
	v_cvt_f32_u32_e32 v119, v119
	v_fmamk_f32 v119, v119, 0xbc83298c, v120
	v_mul_f32_e64 v119, v117, |v119|
	v_mul_f32_e32 v119, 0x3fb8aa3b, v119
	v_exp_f32_e32 v169, v119
	s_add_i32 s30, s29, 18
	v_add_u32_e32 v119, s30, v118
	v_cvt_f32_u32_e32 v119, v119
	v_fmamk_f32 v119, v119, 0xbc83298c, v120
	v_mul_f32_e64 v119, v117, |v119|
	v_mul_f32_e32 v119, 0x3fb8aa3b, v119
	v_exp_f32_e32 v170, v119
	s_add_i32 s30, s29, 19
	v_add_u32_e32 v119, s30, v118
	v_cvt_f32_u32_e32 v119, v119
	v_fmamk_f32 v119, v119, 0xbc83298c, v120
	v_mul_f32_e64 v119, v117, |v119|
	v_mul_f32_e32 v119, 0x3fb8aa3b, v119
	v_exp_f32_e32 v171, v119
	s_add_i32 s30, s29, 24
	v_add_u32_e32 v119, s30, v118
	v_cvt_f32_u32_e32 v119, v119
	v_fmamk_f32 v119, v119, 0xbc83298c, v120
	v_mul_f32_e64 v119, v117, |v119|
	v_mul_f32_e32 v119, 0x3fb8aa3b, v119
	v_exp_f32_e32 v172, v119
	s_add_i32 s30, s29, 25
	v_add_u32_e32 v119, s30, v118
	v_cvt_f32_u32_e32 v119, v119
	v_fmamk_f32 v119, v119, 0xbc83298c, v120
	v_mul_f32_e64 v119, v117, |v119|
	v_mul_f32_e32 v119, 0x3fb8aa3b, v119
	v_exp_f32_e32 v173, v119
	s_add_i32 s30, s29, 26
	v_add_u32_e32 v119, s30, v118
	v_cvt_f32_u32_e32 v119, v119
	v_fmamk_f32 v119, v119, 0xbc83298c, v120
	v_mul_f32_e64 v119, v117, |v119|
	v_mul_f32_e32 v119, 0x3fb8aa3b, v119
	v_exp_f32_e32 v174, v119
	s_add_i32 s30, s29, 27
	v_add_u32_e32 v119, s30, v118
	v_cvt_f32_u32_e32 v119, v119
	v_fmamk_f32 v119, v119, 0xbc83298c, v120
	v_mul_f32_e64 v119, v117, |v119|
	v_mul_f32_e32 v119, 0x3fb8aa3b, v119
	v_exp_f32_e32 v175, v119
	s_nop 7
	v_mul_f32_e32 v176, v96, v160
	s_mov_b64 s[36:37], s[34:35]
	global_store_dword v115, v176, s[36:37] nt
	v_mul_f32_e32 v177, v97, v161
	s_add_u32 s36, s34, 0xc000
	s_addc_u32 s37, s35, 0
	global_store_dword v115, v177, s[36:37] nt
	v_mul_f32_e32 v178, v98, v162
	s_add_u32 s36, s34, 0x18000
; __device__ __forceinline__ void kraw_items(const Args& a, int gw, int NGW, int lane) {
;     ...
;     for (int it = gw; it < 192 * 32; it += NGW) {
;         const int pg = it >> 5, cgp = it & 31, p = pg * 64 + lane, c0 = cgp * 48;
;         float h[64];
; #pragma unroll
;         for (int q = 0; q < 16; ++q) { const f32x4 t = *(const f32x4*)(H3 + (size_t)p * 64 + 4 * q); h[4 * q] = t.x; h[4 * q + 1] = t.y; h[4 * q + 2] = t.z; h[4 * q + 3] = t.w; }
;         const int grp = p >= LP, tpos = p - grp * LP, L = grp ? LS : LP;
;         const float tt = (float)tpos * (1.0f / (float)(L - 1));
; #pragma unroll 1
;         for (int cb = 0; cb < 4; ++cb) {
;             const float* wr = a.in[I_FWOUT] + lane * 1536 + c0 + 12 * cb;
;             const f32x4 w0 = *(const f32x4*)(wr), w1 = *(const f32x4*)(wr + 4), w2 = *(const f32x4*)(wr + 8);
;             float wv[12] = {w0.x, w0.y, w0.z, w0.w, w1.x, w1.y, w1.z, w1.w, w2.x, w2.y, w2.z, w2.w};
;     ...
;                 KR[(size_t)c * (LP + LS) + p] = acc * __expf(-tt * delta); }
	s_addc_u32 s37, s35, 0
	global_store_dword v115, v178, s[36:37] nt
	v_mul_f32_e32 v179, v99, v163
	s_add_u32 s36, s34, 0x24000
	s_addc_u32 s37, s35, 0
	global_store_dword v115, v179, s[36:37] nt
	v_mul_f32_e32 v180, v100, v164
	s_add_u32 s36, s34, 0x60000
	s_addc_u32 s37, s35, 0
	global_store_dword v115, v180, s[36:37] nt
	v_mul_f32_e32 v181, v101, v165
	s_add_u32 s36, s34, 0x6c000
	s_addc_u32 s37, s35, 0
	global_store_dword v115, v181, s[36:37] nt
	v_mul_f32_e32 v182, v102, v166
	s_add_u32 s36, s34, 0x78000
	s_addc_u32 s37, s35, 0
	global_store_dword v115, v182, s[36:37] nt
	v_mul_f32_e32 v183, v103, v167
	s_add_u32 s36, s34, 0x84000
	s_addc_u32 s37, s35, 0
	global_store_dword v115, v183, s[36:37] nt
	v_mul_f32_e32 v184, v104, v168
	s_add_u32 s36, s34, 0xc0000
	s_addc_u32 s37, s35, 0
	global_store_dword v115, v184, s[36:37] nt
	v_mul_f32_e32 v185, v105, v169
	s_add_u32 s36, s34, 0xcc000
	s_addc_u32 s37, s35, 0
	global_store_dword v115, v185, s[36:37] nt
	v_mul_f32_e32 v186, v106, v170
	s_add_u32 s36, s34, 0xd8000
	s_addc_u32 s37, s35, 0
	global_store_dword v115, v186, s[36:37] nt
	v_mul_f32_e32 v187, v107, v171
	s_add_u32 s36, s34, 0xe4000
	s_addc_u32 s37, s35, 0
	global_store_dword v115, v187, s[36:37] nt
	v_mul_f32_e32 v188, v108, v172
	s_add_u32 s36, s34, 0x120000
	s_addc_u32 s37, s35, 0
	global_store_dword v115, v188, s[36:37] nt
	v_mul_f32_e32 v189, v109, v173
	s_add_u32 s36, s34, 0x12c000
	s_addc_u32 s37, s35, 0
	global_store_dword v115, v189, s[36:37] nt
	v_mul_f32_e32 v190, v110, v174
	s_add_u32 s36, s34, 0x138000
	s_addc_u32 s37, s35, 0
	global_store_dword v115, v190, s[36:37] nt
	v_mul_f32_e32 v191, v111, v175
	s_add_u32 s36, s34, 0x144000
	s_addc_u32 s37, s35, 0
	global_store_dword v115, v191, s[36:37] nt
	s_add_i32 s28, s21, 64
	s_sub_i32 s29, s28, 0x300
	s_cmp_ge_u32 s28, 0x300
	s_cselect_b32 s29, s29, s28
	s_mul_i32 s30, s28, 0xc000
	s_lshl_b32 s35, s20, 2
	s_add_u32 s30, s30, s35
	s_add_u32 s34, s14, s30
	s_addc_u32 s35, s15, 0
	s_add_i32 s17, s16, 0x1000
	s_lshr_b32 s18, s17, 4
	s_and_b32 s19, s17, 15
	s_lshl_b32 s20, s18, 5
	s_mul_i32 s21, s19, 0x60
	s_lshl_b32 s30, s20, 8
	s_add_u32 s24, s10, s30
	s_addc_u32 s25, s11, 0
	global_load_dwordx4 v[0:3], v114, s[24:25] offset:0
	global_load_dwordx4 v[4:7], v114, s[24:25] offset:16
	global_load_dwordx4 v[8:11], v114, s[24:25] offset:32
	global_load_dwordx4 v[12:15], v114, s[24:25] offset:48
	global_load_dwordx4 v[16:19], v114, s[24:25] offset:64
	global_load_dwordx4 v[20:23], v114, s[24:25] offset:80
	global_load_dwordx4 v[24:27], v114, s[24:25] offset:96
	global_load_dwordx4 v[28:31], v114, s[24:25] offset:112
	s_add_i32 s30, s21, 0
	s_lshl_b32 s30, s30, 2
	s_add_u32 s26, s6, s30
	s_addc_u32 s27, s7, 0
	global_load_dword v64, v115, s[26:27]
	s_add_u32 s26, s26, 0x1800
	s_addc_u32 s27, s27, 0
	global_load_dword v65, v115, s[26:27]
	s_add_u32 s26, s26, 0x1800
	s_addc_u32 s27, s27, 0
	global_load_dword v66, v115, s[26:27]
	s_add_u32 s26, s26, 0x1800
	s_addc_u32 s27, s27, 0
	global_load_dword v67, v115, s[26:27]
	s_add_u32 s26, s26, 0x1800
	s_addc_u32 s27, s27, 0
	global_load_dword v68, v115, s[26:27]
	s_add_u32 s26, s26, 0x1800
	s_addc_u32 s27, s27, 0
	global_load_dword v69, v115, s[26:27]
	s_add_u32 s26, s26, 0x1800
	s_addc_u32 s27, s27, 0
	global_load_dword v70, v115, s[26:27]
	s_add_u32 s26, s26, 0x1800
	s_addc_u32 s27, s27, 0
	global_load_dword v71, v115, s[26:27]
	s_add_u32 s26, s26, 0x1800
	s_addc_u32 s27, s27, 0
	global_load_dword v72, v115, s[26:27]
	s_add_u32 s26, s26, 0x1800
	s_addc_u32 s27, s27, 0
	global_load_dword v73, v115, s[26:27]
	s_add_u32 s26, s26, 0x1800
	s_addc_u32 s27, s27, 0
	global_load_dword v74, v115, s[26:27]
	s_add_u32 s26, s26, 0x1800
	s_addc_u32 s27, s27, 0
	global_load_dword v75, v115, s[26:27]
	s_add_u32 s26, s26, 0x1800
	s_addc_u32 s27, s27, 0
	global_load_dword v76, v115, s[26:27]
	s_add_u32 s26, s26, 0x1800
	s_addc_u32 s27, s27, 0
	global_load_dword v77, v115, s[26:27]
	s_add_u32 s26, s26, 0x1800
	s_addc_u32 s27, s27, 0
	global_load_dword v78, v115, s[26:27]
	s_add_u32 s26, s26, 0x1800
	s_addc_u32 s27, s27, 0
	global_load_dword v79, v115, s[26:27]
	s_add_u32 s26, s26, 0x1800
	s_addc_u32 s27, s27, 0
	global_load_dword v80, v115, s[26:27]
	s_add_u32 s26, s26, 0x1800
	s_addc_u32 s27, s27, 0
	global_load_dword v81, v115, s[26:27]
	s_add_u32 s26, s26, 0x1800
	s_addc_u32 s27, s27, 0
	global_load_dword v82, v115, s[26:27]
	s_add_u32 s26, s26, 0x1800
	s_addc_u32 s27, s27, 0
	global_load_dword v83, v115, s[26:27]
	s_add_u32 s26, s26, 0x1800
	s_addc_u32 s27, s27, 0
	global_load_dword v84, v115, s[26:27]
	s_add_u32 s26, s26, 0x1800
	s_addc_u32 s27, s27, 0
	global_load_dword v85, v115, s[26:27]
	s_add_u32 s26, s26, 0x1800
	s_addc_u32 s27, s27, 0
	global_load_dword v86, v115, s[26:27]
	s_add_u32 s26, s26, 0x1800
	s_addc_u32 s27, s27, 0
	global_load_dword v87, v115, s[26:27]
	s_add_u32 s26, s26, 0x1800
	s_addc_u32 s27, s27, 0
	global_load_dword v88, v115, s[26:27]
	s_add_u32 s26, s26, 0x1800
	s_addc_u32 s27, s27, 0
	global_load_dword v89, v115, s[26:27]
	s_add_u32 s26, s26, 0x1800
	s_addc_u32 s27, s27, 0
	global_load_dword v90, v115, s[26:27]
	s_add_u32 s26, s26, 0x1800
	s_addc_u32 s27, s27, 0
	global_load_dword v91, v115, s[26:27]
	s_add_u32 s26, s26, 0x1800
	s_addc_u32 s27, s27, 0
	global_load_dword v92, v115, s[26:27]
	s_add_u32 s26, s26, 0x1800
	s_addc_u32 s27, s27, 0
	global_load_dword v93, v115, s[26:27]
	s_add_u32 s26, s26, 0x1800
	s_addc_u32 s27, s27, 0
	global_load_dword v94, v115, s[26:27]
	s_add_u32 s26, s26, 0x1800
	s_addc_u32 s27, s27, 0
	global_load_dword v95, v115, s[26:27]
	s_waitcnt vmcnt(56)
; __device__ __forceinline__ void kraw_items(const Args& a, int gw, int NGW, int lane) {
;     ...
;             for (int ci = 0; ci < 12; ++ci) { const int c = c0 + 12 * cb + ci;
;                 float acc = 0.f;
; #pragma unroll
;                 for (int jj = 0; jj < 64; ++jj) acc += h[jj] * __builtin_bit_cast(float, __builtin_amdgcn_readlane(__builtin_bit_cast(int, wv[ci]), jj));
;                 const int cm = c % 768;
;                 const float delta = fabsf(-3.0701134573253945f + (float)cm * ((-15.350567286626973f + 3.0701134573253945f) / 767.0f));
;                 KR[(size_t)c * (LP + LS) + p] = acc * __expf(-tt * delta); }
	v_mfma_f32_32x32x2_f32 v[96:111], v128, v32, 0
	v_mfma_f32_32x32x2_f32 v[96:111], v129, v33, v[96:111]
	v_mfma_f32_32x32x2_f32 v[96:111], v130, v34, v[96:111]
	v_mfma_f32_32x32x2_f32 v[96:111], v131, v35, v[96:111]
	v_mfma_f32_32x32x2_f32 v[96:111], v132, v36, v[96:111]
	v_mfma_f32_32x32x2_f32 v[96:111], v133, v37, v[96:111]
	v_mfma_f32_32x32x2_f32 v[96:111], v134, v38, v[96:111]
	v_mfma_f32_32x32x2_f32 v[96:111], v135, v39, v[96:111]
	v_mfma_f32_32x32x2_f32 v[96:111], v136, v40, v[96:111]
	v_mfma_f32_32x32x2_f32 v[96:111], v137, v41, v[96:111]
	v_mfma_f32_32x32x2_f32 v[96:111], v138, v42, v[96:111]
	v_mfma_f32_32x32x2_f32 v[96:111], v139, v43, v[96:111]
	v_mfma_f32_32x32x2_f32 v[96:111], v140, v44, v[96:111]
	v_mfma_f32_32x32x2_f32 v[96:111], v141, v45, v[96:111]
	v_mfma_f32_32x32x2_f32 v[96:111], v142, v46, v[96:111]
	v_mfma_f32_32x32x2_f32 v[96:111], v143, v47, v[96:111]
	v_mfma_f32_32x32x2_f32 v[96:111], v144, v48, v[96:111]
	v_mfma_f32_32x32x2_f32 v[96:111], v145, v49, v[96:111]
	v_mfma_f32_32x32x2_f32 v[96:111], v146, v50, v[96:111]
	v_mfma_f32_32x32x2_f32 v[96:111], v147, v51, v[96:111]
	v_mfma_f32_32x32x2_f32 v[96:111], v148, v52, v[96:111]
	v_mfma_f32_32x32x2_f32 v[96:111], v149, v53, v[96:111]
	v_mfma_f32_32x32x2_f32 v[96:111], v150, v54, v[96:111]
	v_mfma_f32_32x32x2_f32 v[96:111], v151, v55, v[96:111]
	v_mfma_f32_32x32x2_f32 v[96:111], v152, v56, v[96:111]
	v_mfma_f32_32x32x2_f32 v[96:111], v153, v57, v[96:111]
	v_mfma_f32_32x32x2_f32 v[96:111], v154, v58, v[96:111]
	v_mfma_f32_32x32x2_f32 v[96:111], v155, v59, v[96:111]
	v_mfma_f32_32x32x2_f32 v[96:111], v156, v60, v[96:111]
	v_mfma_f32_32x32x2_f32 v[96:111], v157, v61, v[96:111]
	v_mfma_f32_32x32x2_f32 v[96:111], v158, v62, v[96:111]
	v_mfma_f32_32x32x2_f32 v[96:111], v159, v63, v[96:111]
	s_add_i32 s30, s29, 0
	v_add_u32_e32 v119, s30, v118
	v_cvt_f32_u32_e32 v119, v119
	v_fmamk_f32 v119, v119, 0xbc83298c, v120
	v_mul_f32_e64 v119, v117, |v119|
	v_mul_f32_e32 v119, 0x3fb8aa3b, v119
	v_exp_f32_e32 v160, v119
	s_add_i32 s30, s29, 1
	v_add_u32_e32 v119, s30, v118
	v_cvt_f32_u32_e32 v119, v119
	v_fmamk_f32 v119, v119, 0xbc83298c, v120
	v_mul_f32_e64 v119, v117, |v119|
	v_mul_f32_e32 v119, 0x3fb8aa3b, v119
	v_exp_f32_e32 v161, v119
	s_add_i32 s30, s29, 2
	v_add_u32_e32 v119, s30, v118
	v_cvt_f32_u32_e32 v119, v119
	v_fmamk_f32 v119, v119, 0xbc83298c, v120
	v_mul_f32_e64 v119, v117, |v119|
	v_mul_f32_e32 v119, 0x3fb8aa3b, v119
	v_exp_f32_e32 v162, v119
	s_add_i32 s30, s29, 3
	v_add_u32_e32 v119, s30, v118
	v_cvt_f32_u32_e32 v119, v119
	v_fmamk_f32 v119, v119, 0xbc83298c, v120
	v_mul_f32_e64 v119, v117, |v119|
	v_mul_f32_e32 v119, 0x3fb8aa3b, v119
	v_exp_f32_e32 v163, v119
	s_add_i32 s30, s29, 8
	v_add_u32_e32 v119, s30, v118
	v_cvt_f32_u32_e32 v119, v119
	v_fmamk_f32 v119, v119, 0xbc83298c, v120
	v_mul_f32_e64 v119, v117, |v119|
	v_mul_f32_e32 v119, 0x3fb8aa3b, v119
	v_exp_f32_e32 v164, v119
	s_add_i32 s30, s29, 9
	v_add_u32_e32 v119, s30, v118
	v_cvt_f32_u32_e32 v119, v119
	v_fmamk_f32 v119, v119, 0xbc83298c, v120
	v_mul_f32_e64 v119, v117, |v119|
	v_mul_f32_e32 v119, 0x3fb8aa3b, v119
	v_exp_f32_e32 v165, v119
	s_add_i32 s30, s29, 10
	v_add_u32_e32 v119, s30, v118
	v_cvt_f32_u32_e32 v119, v119
	v_fmamk_f32 v119, v119, 0xbc83298c, v120
	v_mul_f32_e64 v119, v117, |v119|
	v_mul_f32_e32 v119, 0x3fb8aa3b, v119
	v_exp_f32_e32 v166, v119
	s_add_i32 s30, s29, 11
	v_add_u32_e32 v119, s30, v118
	v_cvt_f32_u32_e32 v119, v119
	v_fmamk_f32 v119, v119, 0xbc83298c, v120
	v_mul_f32_e64 v119, v117, |v119|
	v_mul_f32_e32 v119, 0x3fb8aa3b, v119
	v_exp_f32_e32 v167, v119
	s_add_i32 s30, s29, 16
	v_add_u32_e32 v119, s30, v118
	v_cvt_f32_u32_e32 v119, v119
	v_fmamk_f32 v119, v119, 0xbc83298c, v120
	v_mul_f32_e64 v119, v117, |v119|
	v_mul_f32_e32 v119, 0x3fb8aa3b, v119
	v_exp_f32_e32 v168, v119
	s_add_i32 s30, s29, 17
	v_add_u32_e32 v119, s30, v118
	v_cvt_f32_u32_e32 v119, v119
	v_fmamk_f32 v119, v119, 0xbc83298c, v120
	v_mul_f32_e64 v119, v117, |v119|
	v_mul_f32_e32 v119, 0x3fb8aa3b, v119
	v_exp_f32_e32 v169, v119
	s_add_i32 s30, s29, 18
	v_add_u32_e32 v119, s30, v118
	v_cvt_f32_u32_e32 v119, v119
	v_fmamk_f32 v119, v119, 0xbc83298c, v120
	v_mul_f32_e64 v119, v117, |v119|
	v_mul_f32_e32 v119, 0x3fb8aa3b, v119
	v_exp_f32_e32 v170, v119
	s_add_i32 s30, s29, 19
	v_add_u32_e32 v119, s30, v118
	v_cvt_f32_u32_e32 v119, v119
	v_fmamk_f32 v119, v119, 0xbc83298c, v120
	v_mul_f32_e64 v119, v117, |v119|
	v_mul_f32_e32 v119, 0x3fb8aa3b, v119
	v_exp_f32_e32 v171, v119
	s_add_i32 s30, s29, 24
	v_add_u32_e32 v119, s30, v118
	v_cvt_f32_u32_e32 v119, v119
	v_fmamk_f32 v119, v119, 0xbc83298c, v120
	v_mul_f32_e64 v119, v117, |v119|
	v_mul_f32_e32 v119, 0x3fb8aa3b, v119
	v_exp_f32_e32 v172, v119
	s_add_i32 s30, s29, 25
	v_add_u32_e32 v119, s30, v118
	v_cvt_f32_u32_e32 v119, v119
	v_fmamk_f32 v119, v119, 0xbc83298c, v120
	v_mul_f32_e64 v119, v117, |v119|
	v_mul_f32_e32 v119, 0x3fb8aa3b, v119
	v_exp_f32_e32 v173, v119
	s_add_i32 s30, s29, 26
	v_add_u32_e32 v119, s30, v118
	v_cvt_f32_u32_e32 v119, v119
	v_fmamk_f32 v119, v119, 0xbc83298c, v120
	v_mul_f32_e64 v119, v117, |v119|
	v_mul_f32_e32 v119, 0x3fb8aa3b, v119
	v_exp_f32_e32 v174, v119
	s_add_i32 s30, s29, 27
	v_add_u32_e32 v119, s30, v118
	v_cvt_f32_u32_e32 v119, v119
	v_fmamk_f32 v119, v119, 0xbc83298c, v120
	v_mul_f32_e64 v119, v117, |v119|
	v_mul_f32_e32 v119, 0x3fb8aa3b, v119
	v_exp_f32_e32 v175, v119
	s_nop 7
	v_mul_f32_e32 v176, v96, v160
	s_mov_b64 s[36:37], s[34:35]
	global_store_dword v115, v176, s[36:37] nt
	v_mul_f32_e32 v177, v97, v161
	s_add_u32 s36, s34, 0xc000
	s_addc_u32 s37, s35, 0
	global_store_dword v115, v177, s[36:37] nt
	v_mul_f32_e32 v178, v98, v162
; __device__ __forceinline__ void kraw_items(const Args& a, int gw, int NGW, int lane) {
;     ...
;         const int grp = p >= LP, tpos = p - grp * LP, L = grp ? LS : LP;
;         const float tt = (float)tpos * (1.0f / (float)(L - 1));
;     ...
;             const float* wr = a.in[I_FWOUT] + lane * 1536 + c0 + 12 * cb;
;             const f32x4 w0 = *(const f32x4*)(wr), w1 = *(const f32x4*)(wr + 4), w2 = *(const f32x4*)(wr + 8);
;             float wv[12] = {w0.x, w0.y, w0.z, w0.w, w1.x, w1.y, w1.z, w1.w, w2.x, w2.y, w2.z, w2.w};
;     ...
;                 KR[(size_t)c * (LP + LS) + p] = acc * __expf(-tt * delta); }
	s_add_u32 s36, s34, 0x18000
	s_addc_u32 s37, s35, 0
	global_store_dword v115, v178, s[36:37] nt
	v_mul_f32_e32 v179, v99, v163
	s_add_u32 s36, s34, 0x24000
	s_addc_u32 s37, s35, 0
	global_store_dword v115, v179, s[36:37] nt
	v_mul_f32_e32 v180, v100, v164
	s_add_u32 s36, s34, 0x60000
	s_addc_u32 s37, s35, 0
	global_store_dword v115, v180, s[36:37] nt
	v_mul_f32_e32 v181, v101, v165
	s_add_u32 s36, s34, 0x6c000
	s_addc_u32 s37, s35, 0
	global_store_dword v115, v181, s[36:37] nt
	v_mul_f32_e32 v182, v102, v166
	s_add_u32 s36, s34, 0x78000
	s_addc_u32 s37, s35, 0
	global_store_dword v115, v182, s[36:37] nt
	v_mul_f32_e32 v183, v103, v167
	s_add_u32 s36, s34, 0x84000
	s_addc_u32 s37, s35, 0
	global_store_dword v115, v183, s[36:37] nt
	v_mul_f32_e32 v184, v104, v168
	s_add_u32 s36, s34, 0xc0000
	s_addc_u32 s37, s35, 0
	global_store_dword v115, v184, s[36:37] nt
	v_mul_f32_e32 v185, v105, v169
	s_add_u32 s36, s34, 0xcc000
	s_addc_u32 s37, s35, 0
	global_store_dword v115, v185, s[36:37] nt
	v_mul_f32_e32 v186, v106, v170
	s_add_u32 s36, s34, 0xd8000
	s_addc_u32 s37, s35, 0
	global_store_dword v115, v186, s[36:37] nt
	v_mul_f32_e32 v187, v107, v171
	s_add_u32 s36, s34, 0xe4000
	s_addc_u32 s37, s35, 0
	global_store_dword v115, v187, s[36:37] nt
	v_mul_f32_e32 v188, v108, v172
	s_add_u32 s36, s34, 0x120000
	s_addc_u32 s37, s35, 0
	global_store_dword v115, v188, s[36:37] nt
	v_mul_f32_e32 v189, v109, v173
	s_add_u32 s36, s34, 0x12c000
	s_addc_u32 s37, s35, 0
	global_store_dword v115, v189, s[36:37] nt
	v_mul_f32_e32 v190, v110, v174
	s_add_u32 s36, s34, 0x138000
	s_addc_u32 s37, s35, 0
	global_store_dword v115, v190, s[36:37] nt
	v_mul_f32_e32 v191, v111, v175
	s_add_u32 s36, s34, 0x144000
	s_addc_u32 s37, s35, 0
	global_store_dword v115, v191, s[36:37] nt
	s_add_i32 s28, s21, 0
	s_sub_i32 s29, s28, 0x300
	s_cmp_ge_u32 s28, 0x300
	s_cselect_b32 s29, s29, s28
	s_mul_i32 s30, s28, 0xc000
	s_lshl_b32 s35, s20, 2
	s_add_u32 s30, s30, s35
	s_add_u32 s34, s14, s30
	s_addc_u32 s35, s15, 0
	s_mov_b32 s22, 0xb9000400
	s_cmp_ge_u32 s20, 0x2000
	s_cselect_b32 s22, 0xb9800801, s22
	s_and_b32 s30, s20, 0x1fff
	v_add_u32_e32 v119, s30, v112
	v_cvt_f32_u32_e32 v119, v119
	v_mul_f32_e32 v117, s22, v119
	s_add_i32 s30, s21, 32
	s_lshl_b32 s30, s30, 2
	s_add_u32 s26, s6, s30
	s_addc_u32 s27, s7, 0
	global_load_dword v128, v115, s[26:27]
	s_add_u32 s26, s26, 0x1800
	s_addc_u32 s27, s27, 0
	global_load_dword v129, v115, s[26:27]
	s_add_u32 s26, s26, 0x1800
	s_addc_u32 s27, s27, 0
	global_load_dword v130, v115, s[26:27]
	s_add_u32 s26, s26, 0x1800
	s_addc_u32 s27, s27, 0
	global_load_dword v131, v115, s[26:27]
	s_add_u32 s26, s26, 0x1800
	s_addc_u32 s27, s27, 0
	global_load_dword v132, v115, s[26:27]
	s_add_u32 s26, s26, 0x1800
	s_addc_u32 s27, s27, 0
	global_load_dword v133, v115, s[26:27]
	s_add_u32 s26, s26, 0x1800
	s_addc_u32 s27, s27, 0
	global_load_dword v134, v115, s[26:27]
	s_add_u32 s26, s26, 0x1800
	s_addc_u32 s27, s27, 0
	global_load_dword v135, v115, s[26:27]
	s_add_u32 s26, s26, 0x1800
	s_addc_u32 s27, s27, 0
	global_load_dword v136, v115, s[26:27]
	s_add_u32 s26, s26, 0x1800
	s_addc_u32 s27, s27, 0
	global_load_dword v137, v115, s[26:27]
	s_add_u32 s26, s26, 0x1800
	s_addc_u32 s27, s27, 0
	global_load_dword v138, v115, s[26:27]
	s_add_u32 s26, s26, 0x1800
	s_addc_u32 s27, s27, 0
	global_load_dword v139, v115, s[26:27]
	s_add_u32 s26, s26, 0x1800
	s_addc_u32 s27, s27, 0
	global_load_dword v140, v115, s[26:27]
	s_add_u32 s26, s26, 0x1800
	s_addc_u32 s27, s27, 0
	global_load_dword v141, v115, s[26:27]
	s_add_u32 s26, s26, 0x1800
	s_addc_u32 s27, s27, 0
	global_load_dword v142, v115, s[26:27]
	s_add_u32 s26, s26, 0x1800
	s_addc_u32 s27, s27, 0
	global_load_dword v143, v115, s[26:27]
	s_add_u32 s26, s26, 0x1800
	s_addc_u32 s27, s27, 0
	global_load_dword v144, v115, s[26:27]
	s_add_u32 s26, s26, 0x1800
	s_addc_u32 s27, s27, 0
	global_load_dword v145, v115, s[26:27]
	s_add_u32 s26, s26, 0x1800
	s_addc_u32 s27, s27, 0
	global_load_dword v146, v115, s[26:27]
	s_add_u32 s26, s26, 0x1800
	s_addc_u32 s27, s27, 0
	global_load_dword v147, v115, s[26:27]
	s_add_u32 s26, s26, 0x1800
	s_addc_u32 s27, s27, 0
	global_load_dword v148, v115, s[26:27]
	s_add_u32 s26, s26, 0x1800
	s_addc_u32 s27, s27, 0
	global_load_dword v149, v115, s[26:27]
	s_add_u32 s26, s26, 0x1800
	s_addc_u32 s27, s27, 0
	global_load_dword v150, v115, s[26:27]
	s_add_u32 s26, s26, 0x1800
	s_addc_u32 s27, s27, 0
	global_load_dword v151, v115, s[26:27]
	s_add_u32 s26, s26, 0x1800
	s_addc_u32 s27, s27, 0
	global_load_dword v152, v115, s[26:27]
	s_add_u32 s26, s26, 0x1800
	s_addc_u32 s27, s27, 0
	global_load_dword v153, v115, s[26:27]
	s_add_u32 s26, s26, 0x1800
	s_addc_u32 s27, s27, 0
	global_load_dword v154, v115, s[26:27]
	s_add_u32 s26, s26, 0x1800
	s_addc_u32 s27, s27, 0
	global_load_dword v155, v115, s[26:27]
	s_add_u32 s26, s26, 0x1800
	s_addc_u32 s27, s27, 0
	global_load_dword v156, v115, s[26:27]
	s_add_u32 s26, s26, 0x1800
	s_addc_u32 s27, s27, 0
	global_load_dword v157, v115, s[26:27]
	s_add_u32 s26, s26, 0x1800
	s_addc_u32 s27, s27, 0
	global_load_dword v158, v115, s[26:27]
	s_add_u32 s26, s26, 0x1800
	s_addc_u32 s27, s27, 0
	global_load_dword v159, v115, s[26:27]
	s_waitcnt vmcnt(48)
; __device__ __forceinline__ void kraw_items(const Args& a, int gw, int NGW, int lane) {
;     ...
;             for (int ci = 0; ci < 12; ++ci) { const int c = c0 + 12 * cb + ci;
;                 float acc = 0.f;
; #pragma unroll
;                 for (int jj = 0; jj < 64; ++jj) acc += h[jj] * __builtin_bit_cast(float, __builtin_amdgcn_readlane(__builtin_bit_cast(int, wv[ci]), jj));
;                 const int cm = c % 768;
;                 const float delta = fabsf(-3.0701134573253945f + (float)cm * ((-15.350567286626973f + 3.0701134573253945f) / 767.0f));
;                 KR[(size_t)c * (LP + LS) + p] = acc * __expf(-tt * delta); }
	v_mfma_f32_32x32x2_f32 v[96:111], v64, v0, 0
	v_mfma_f32_32x32x2_f32 v[96:111], v65, v1, v[96:111]
	v_mfma_f32_32x32x2_f32 v[96:111], v66, v2, v[96:111]
	v_mfma_f32_32x32x2_f32 v[96:111], v67, v3, v[96:111]
	v_mfma_f32_32x32x2_f32 v[96:111], v68, v4, v[96:111]
	v_mfma_f32_32x32x2_f32 v[96:111], v69, v5, v[96:111]
	v_mfma_f32_32x32x2_f32 v[96:111], v70, v6, v[96:111]
	v_mfma_f32_32x32x2_f32 v[96:111], v71, v7, v[96:111]
	v_mfma_f32_32x32x2_f32 v[96:111], v72, v8, v[96:111]
	v_mfma_f32_32x32x2_f32 v[96:111], v73, v9, v[96:111]
	v_mfma_f32_32x32x2_f32 v[96:111], v74, v10, v[96:111]
	v_mfma_f32_32x32x2_f32 v[96:111], v75, v11, v[96:111]
	v_mfma_f32_32x32x2_f32 v[96:111], v76, v12, v[96:111]
	v_mfma_f32_32x32x2_f32 v[96:111], v77, v13, v[96:111]
	v_mfma_f32_32x32x2_f32 v[96:111], v78, v14, v[96:111]
	v_mfma_f32_32x32x2_f32 v[96:111], v79, v15, v[96:111]
	v_mfma_f32_32x32x2_f32 v[96:111], v80, v16, v[96:111]
	v_mfma_f32_32x32x2_f32 v[96:111], v81, v17, v[96:111]
	v_mfma_f32_32x32x2_f32 v[96:111], v82, v18, v[96:111]
	v_mfma_f32_32x32x2_f32 v[96:111], v83, v19, v[96:111]
	v_mfma_f32_32x32x2_f32 v[96:111], v84, v20, v[96:111]
	v_mfma_f32_32x32x2_f32 v[96:111], v85, v21, v[96:111]
	v_mfma_f32_32x32x2_f32 v[96:111], v86, v22, v[96:111]
	v_mfma_f32_32x32x2_f32 v[96:111], v87, v23, v[96:111]
	v_mfma_f32_32x32x2_f32 v[96:111], v88, v24, v[96:111]
	v_mfma_f32_32x32x2_f32 v[96:111], v89, v25, v[96:111]
	v_mfma_f32_32x32x2_f32 v[96:111], v90, v26, v[96:111]
	v_mfma_f32_32x32x2_f32 v[96:111], v91, v27, v[96:111]
	v_mfma_f32_32x32x2_f32 v[96:111], v92, v28, v[96:111]
	v_mfma_f32_32x32x2_f32 v[96:111], v93, v29, v[96:111]
	v_mfma_f32_32x32x2_f32 v[96:111], v94, v30, v[96:111]
	v_mfma_f32_32x32x2_f32 v[96:111], v95, v31, v[96:111]
	s_add_i32 s30, s29, 0
	v_add_u32_e32 v119, s30, v118
	v_cvt_f32_u32_e32 v119, v119
	v_fmamk_f32 v119, v119, 0xbc83298c, v120
	v_mul_f32_e64 v119, v117, |v119|
	v_mul_f32_e32 v119, 0x3fb8aa3b, v119
	v_exp_f32_e32 v160, v119
	s_add_i32 s30, s29, 1
	v_add_u32_e32 v119, s30, v118
	v_cvt_f32_u32_e32 v119, v119
	v_fmamk_f32 v119, v119, 0xbc83298c, v120
	v_mul_f32_e64 v119, v117, |v119|
	v_mul_f32_e32 v119, 0x3fb8aa3b, v119
	v_exp_f32_e32 v161, v119
	s_add_i32 s30, s29, 2
	v_add_u32_e32 v119, s30, v118
	v_cvt_f32_u32_e32 v119, v119
	v_fmamk_f32 v119, v119, 0xbc83298c, v120
	v_mul_f32_e64 v119, v117, |v119|
	v_mul_f32_e32 v119, 0x3fb8aa3b, v119
	v_exp_f32_e32 v162, v119
	s_add_i32 s30, s29, 3
	v_add_u32_e32 v119, s30, v118
	v_cvt_f32_u32_e32 v119, v119
	v_fmamk_f32 v119, v119, 0xbc83298c, v120
	v_mul_f32_e64 v119, v117, |v119|
	v_mul_f32_e32 v119, 0x3fb8aa3b, v119
	v_exp_f32_e32 v163, v119
	s_add_i32 s30, s29, 8
	v_add_u32_e32 v119, s30, v118
	v_cvt_f32_u32_e32 v119, v119
	v_fmamk_f32 v119, v119, 0xbc83298c, v120
	v_mul_f32_e64 v119, v117, |v119|
	v_mul_f32_e32 v119, 0x3fb8aa3b, v119
	v_exp_f32_e32 v164, v119
	s_add_i32 s30, s29, 9
	v_add_u32_e32 v119, s30, v118
	v_cvt_f32_u32_e32 v119, v119
	v_fmamk_f32 v119, v119, 0xbc83298c, v120
	v_mul_f32_e64 v119, v117, |v119|
	v_mul_f32_e32 v119, 0x3fb8aa3b, v119
	v_exp_f32_e32 v165, v119
	s_add_i32 s30, s29, 10
	v_add_u32_e32 v119, s30, v118
	v_cvt_f32_u32_e32 v119, v119
	v_fmamk_f32 v119, v119, 0xbc83298c, v120
	v_mul_f32_e64 v119, v117, |v119|
	v_mul_f32_e32 v119, 0x3fb8aa3b, v119
	v_exp_f32_e32 v166, v119
	s_add_i32 s30, s29, 11
	v_add_u32_e32 v119, s30, v118
	v_cvt_f32_u32_e32 v119, v119
	v_fmamk_f32 v119, v119, 0xbc83298c, v120
	v_mul_f32_e64 v119, v117, |v119|
	v_mul_f32_e32 v119, 0x3fb8aa3b, v119
	v_exp_f32_e32 v167, v119
	s_add_i32 s30, s29, 16
	v_add_u32_e32 v119, s30, v118
	v_cvt_f32_u32_e32 v119, v119
	v_fmamk_f32 v119, v119, 0xbc83298c, v120
	v_mul_f32_e64 v119, v117, |v119|
	v_mul_f32_e32 v119, 0x3fb8aa3b, v119
	v_exp_f32_e32 v168, v119
	s_add_i32 s30, s29, 17
	v_add_u32_e32 v119, s30, v118
	v_cvt_f32_u32_e32 v119, v119
	v_fmamk_f32 v119, v119, 0xbc83298c, v120
	v_mul_f32_e64 v119, v117, |v119|
	v_mul_f32_e32 v119, 0x3fb8aa3b, v119
	v_exp_f32_e32 v169, v119
	s_add_i32 s30, s29, 18
	v_add_u32_e32 v119, s30, v118
	v_cvt_f32_u32_e32 v119, v119
	v_fmamk_f32 v119, v119, 0xbc83298c, v120
	v_mul_f32_e64 v119, v117, |v119|
	v_mul_f32_e32 v119, 0x3fb8aa3b, v119
	v_exp_f32_e32 v170, v119
	s_add_i32 s30, s29, 19
	v_add_u32_e32 v119, s30, v118
	v_cvt_f32_u32_e32 v119, v119
	v_fmamk_f32 v119, v119, 0xbc83298c, v120
	v_mul_f32_e64 v119, v117, |v119|
	v_mul_f32_e32 v119, 0x3fb8aa3b, v119
	v_exp_f32_e32 v171, v119
	s_add_i32 s30, s29, 24
	v_add_u32_e32 v119, s30, v118
	v_cvt_f32_u32_e32 v119, v119
	v_fmamk_f32 v119, v119, 0xbc83298c, v120
	v_mul_f32_e64 v119, v117, |v119|
	v_mul_f32_e32 v119, 0x3fb8aa3b, v119
	v_exp_f32_e32 v172, v119
	s_add_i32 s30, s29, 25
	v_add_u32_e32 v119, s30, v118
	v_cvt_f32_u32_e32 v119, v119
	v_fmamk_f32 v119, v119, 0xbc83298c, v120
	v_mul_f32_e64 v119, v117, |v119|
	v_mul_f32_e32 v119, 0x3fb8aa3b, v119
	v_exp_f32_e32 v173, v119
	s_add_i32 s30, s29, 26
	v_add_u32_e32 v119, s30, v118
	v_cvt_f32_u32_e32 v119, v119
	v_fmamk_f32 v119, v119, 0xbc83298c, v120
	v_mul_f32_e64 v119, v117, |v119|
	v_mul_f32_e32 v119, 0x3fb8aa3b, v119
	v_exp_f32_e32 v174, v119
	s_add_i32 s30, s29, 27
	v_add_u32_e32 v119, s30, v118
	v_cvt_f32_u32_e32 v119, v119
	v_fmamk_f32 v119, v119, 0xbc83298c, v120
	v_mul_f32_e64 v119, v117, |v119|
	v_mul_f32_e32 v119, 0x3fb8aa3b, v119
	v_exp_f32_e32 v175, v119
	s_nop 7
	v_mul_f32_e32 v176, v96, v160
	s_mov_b64 s[36:37], s[34:35]
	global_store_dword v115, v176, s[36:37] nt
	v_mul_f32_e32 v177, v97, v161
	s_add_u32 s36, s34, 0xc000
	s_addc_u32 s37, s35, 0
	global_store_dword v115, v177, s[36:37] nt
	v_mul_f32_e32 v178, v98, v162
	s_add_u32 s36, s34, 0x18000
; __device__ __forceinline__ void kraw_items(const Args& a, int gw, int NGW, int lane) {
;     ...
;             const float* wr = a.in[I_FWOUT] + lane * 1536 + c0 + 12 * cb;
;             const f32x4 w0 = *(const f32x4*)(wr), w1 = *(const f32x4*)(wr + 4), w2 = *(const f32x4*)(wr + 8);
;             float wv[12] = {w0.x, w0.y, w0.z, w0.w, w1.x, w1.y, w1.z, w1.w, w2.x, w2.y, w2.z, w2.w};
;     ...
;                 KR[(size_t)c * (LP + LS) + p] = acc * __expf(-tt * delta); }
	s_addc_u32 s37, s35, 0
	global_store_dword v115, v178, s[36:37] nt
	v_mul_f32_e32 v179, v99, v163
	s_add_u32 s36, s34, 0x24000
	s_addc_u32 s37, s35, 0
	global_store_dword v115, v179, s[36:37] nt
	v_mul_f32_e32 v180, v100, v164
	s_add_u32 s36, s34, 0x60000
	s_addc_u32 s37, s35, 0
	global_store_dword v115, v180, s[36:37] nt
	v_mul_f32_e32 v181, v101, v165
	s_add_u32 s36, s34, 0x6c000
	s_addc_u32 s37, s35, 0
	global_store_dword v115, v181, s[36:37] nt
	v_mul_f32_e32 v182, v102, v166
	s_add_u32 s36, s34, 0x78000
	s_addc_u32 s37, s35, 0
	global_store_dword v115, v182, s[36:37] nt
	v_mul_f32_e32 v183, v103, v167
	s_add_u32 s36, s34, 0x84000
	s_addc_u32 s37, s35, 0
	global_store_dword v115, v183, s[36:37] nt
	v_mul_f32_e32 v184, v104, v168
	s_add_u32 s36, s34, 0xc0000
	s_addc_u32 s37, s35, 0
	global_store_dword v115, v184, s[36:37] nt
	v_mul_f32_e32 v185, v105, v169
	s_add_u32 s36, s34, 0xcc000
	s_addc_u32 s37, s35, 0
	global_store_dword v115, v185, s[36:37] nt
	v_mul_f32_e32 v186, v106, v170
	s_add_u32 s36, s34, 0xd8000
	s_addc_u32 s37, s35, 0
	global_store_dword v115, v186, s[36:37] nt
	v_mul_f32_e32 v187, v107, v171
	s_add_u32 s36, s34, 0xe4000
	s_addc_u32 s37, s35, 0
	global_store_dword v115, v187, s[36:37] nt
	v_mul_f32_e32 v188, v108, v172
	s_add_u32 s36, s34, 0x120000
	s_addc_u32 s37, s35, 0
	global_store_dword v115, v188, s[36:37] nt
	v_mul_f32_e32 v189, v109, v173
	s_add_u32 s36, s34, 0x12c000
	s_addc_u32 s37, s35, 0
	global_store_dword v115, v189, s[36:37] nt
	v_mul_f32_e32 v190, v110, v174
	s_add_u32 s36, s34, 0x138000
	s_addc_u32 s37, s35, 0
	global_store_dword v115, v190, s[36:37] nt
	v_mul_f32_e32 v191, v111, v175
	s_add_u32 s36, s34, 0x144000
	s_addc_u32 s37, s35, 0
	global_store_dword v115, v191, s[36:37] nt
	s_add_i32 s28, s21, 32
	s_sub_i32 s29, s28, 0x300
	s_cmp_ge_u32 s28, 0x300
	s_cselect_b32 s29, s29, s28
	s_mul_i32 s30, s28, 0xc000
	s_lshl_b32 s35, s20, 2
	s_add_u32 s30, s30, s35
	s_add_u32 s34, s14, s30
	s_addc_u32 s35, s15, 0
	s_add_i32 s30, s21, 64
	s_lshl_b32 s30, s30, 2
	s_add_u32 s26, s6, s30
	s_addc_u32 s27, s7, 0
	global_load_dword v64, v115, s[26:27]
	s_add_u32 s26, s26, 0x1800
	s_addc_u32 s27, s27, 0
	global_load_dword v65, v115, s[26:27]
	s_add_u32 s26, s26, 0x1800
	s_addc_u32 s27, s27, 0
	global_load_dword v66, v115, s[26:27]
	s_add_u32 s26, s26, 0x1800
	s_addc_u32 s27, s27, 0
	global_load_dword v67, v115, s[26:27]
	s_add_u32 s26, s26, 0x1800
	s_addc_u32 s27, s27, 0
	global_load_dword v68, v115, s[26:27]
	s_add_u32 s26, s26, 0x1800
	s_addc_u32 s27, s27, 0
	global_load_dword v69, v115, s[26:27]
	s_add_u32 s26, s26, 0x1800
	s_addc_u32 s27, s27, 0
	global_load_dword v70, v115, s[26:27]
	s_add_u32 s26, s26, 0x1800
	s_addc_u32 s27, s27, 0
	global_load_dword v71, v115, s[26:27]
	s_add_u32 s26, s26, 0x1800
	s_addc_u32 s27, s27, 0
	global_load_dword v72, v115, s[26:27]
	s_add_u32 s26, s26, 0x1800
	s_addc_u32 s27, s27, 0
	global_load_dword v73, v115, s[26:27]
	s_add_u32 s26, s26, 0x1800
	s_addc_u32 s27, s27, 0
	global_load_dword v74, v115, s[26:27]
	s_add_u32 s26, s26, 0x1800
	s_addc_u32 s27, s27, 0
	global_load_dword v75, v115, s[26:27]
	s_add_u32 s26, s26, 0x1800
	s_addc_u32 s27, s27, 0
	global_load_dword v76, v115, s[26:27]
	s_add_u32 s26, s26, 0x1800
	s_addc_u32 s27, s27, 0
	global_load_dword v77, v115, s[26:27]
	s_add_u32 s26, s26, 0x1800
	s_addc_u32 s27, s27, 0
	global_load_dword v78, v115, s[26:27]
	s_add_u32 s26, s26, 0x1800
	s_addc_u32 s27, s27, 0
	global_load_dword v79, v115, s[26:27]
	s_add_u32 s26, s26, 0x1800
	s_addc_u32 s27, s27, 0
	global_load_dword v80, v115, s[26:27]
	s_add_u32 s26, s26, 0x1800
	s_addc_u32 s27, s27, 0
	global_load_dword v81, v115, s[26:27]
	s_add_u32 s26, s26, 0x1800
	s_addc_u32 s27, s27, 0
	global_load_dword v82, v115, s[26:27]
	s_add_u32 s26, s26, 0x1800
	s_addc_u32 s27, s27, 0
	global_load_dword v83, v115, s[26:27]
	s_add_u32 s26, s26, 0x1800
	s_addc_u32 s27, s27, 0
	global_load_dword v84, v115, s[26:27]
	s_add_u32 s26, s26, 0x1800
	s_addc_u32 s27, s27, 0
	global_load_dword v85, v115, s[26:27]
	s_add_u32 s26, s26, 0x1800
	s_addc_u32 s27, s27, 0
	global_load_dword v86, v115, s[26:27]
	s_add_u32 s26, s26, 0x1800
	s_addc_u32 s27, s27, 0
	global_load_dword v87, v115, s[26:27]
	s_add_u32 s26, s26, 0x1800
	s_addc_u32 s27, s27, 0
	global_load_dword v88, v115, s[26:27]
	s_add_u32 s26, s26, 0x1800
	s_addc_u32 s27, s27, 0
	global_load_dword v89, v115, s[26:27]
	s_add_u32 s26, s26, 0x1800
	s_addc_u32 s27, s27, 0
	global_load_dword v90, v115, s[26:27]
	s_add_u32 s26, s26, 0x1800
	s_addc_u32 s27, s27, 0
	global_load_dword v91, v115, s[26:27]
	s_add_u32 s26, s26, 0x1800
	s_addc_u32 s27, s27, 0
	global_load_dword v92, v115, s[26:27]
	s_add_u32 s26, s26, 0x1800
	s_addc_u32 s27, s27, 0
	global_load_dword v93, v115, s[26:27]
	s_add_u32 s26, s26, 0x1800
	s_addc_u32 s27, s27, 0
	global_load_dword v94, v115, s[26:27]
	s_add_u32 s26, s26, 0x1800
	s_addc_u32 s27, s27, 0
	global_load_dword v95, v115, s[26:27]
	s_waitcnt vmcnt(48)
; __device__ __forceinline__ void kraw_items(const Args& a, int gw, int NGW, int lane) {
;     ...
;             for (int ci = 0; ci < 12; ++ci) { const int c = c0 + 12 * cb + ci;
;                 float acc = 0.f;
; #pragma unroll
;                 for (int jj = 0; jj < 64; ++jj) acc += h[jj] * __builtin_bit_cast(float, __builtin_amdgcn_readlane(__builtin_bit_cast(int, wv[ci]), jj));
;                 const int cm = c % 768;
;                 const float delta = fabsf(-3.0701134573253945f + (float)cm * ((-15.350567286626973f + 3.0701134573253945f) / 767.0f));
;                 KR[(size_t)c * (LP + LS) + p] = acc * __expf(-tt * delta); }
	v_mfma_f32_32x32x2_f32 v[96:111], v128, v0, 0
	v_mfma_f32_32x32x2_f32 v[96:111], v129, v1, v[96:111]
	v_mfma_f32_32x32x2_f32 v[96:111], v130, v2, v[96:111]
	v_mfma_f32_32x32x2_f32 v[96:111], v131, v3, v[96:111]
	v_mfma_f32_32x32x2_f32 v[96:111], v132, v4, v[96:111]
	v_mfma_f32_32x32x2_f32 v[96:111], v133, v5, v[96:111]
	v_mfma_f32_32x32x2_f32 v[96:111], v134, v6, v[96:111]
	v_mfma_f32_32x32x2_f32 v[96:111], v135, v7, v[96:111]
	v_mfma_f32_32x32x2_f32 v[96:111], v136, v8, v[96:111]
	v_mfma_f32_32x32x2_f32 v[96:111], v137, v9, v[96:111]
	v_mfma_f32_32x32x2_f32 v[96:111], v138, v10, v[96:111]
	v_mfma_f32_32x32x2_f32 v[96:111], v139, v11, v[96:111]
	v_mfma_f32_32x32x2_f32 v[96:111], v140, v12, v[96:111]
	v_mfma_f32_32x32x2_f32 v[96:111], v141, v13, v[96:111]
	v_mfma_f32_32x32x2_f32 v[96:111], v142, v14, v[96:111]
	v_mfma_f32_32x32x2_f32 v[96:111], v143, v15, v[96:111]
	v_mfma_f32_32x32x2_f32 v[96:111], v144, v16, v[96:111]
	v_mfma_f32_32x32x2_f32 v[96:111], v145, v17, v[96:111]
	v_mfma_f32_32x32x2_f32 v[96:111], v146, v18, v[96:111]
	v_mfma_f32_32x32x2_f32 v[96:111], v147, v19, v[96:111]
	v_mfma_f32_32x32x2_f32 v[96:111], v148, v20, v[96:111]
	v_mfma_f32_32x32x2_f32 v[96:111], v149, v21, v[96:111]
	v_mfma_f32_32x32x2_f32 v[96:111], v150, v22, v[96:111]
	v_mfma_f32_32x32x2_f32 v[96:111], v151, v23, v[96:111]
	v_mfma_f32_32x32x2_f32 v[96:111], v152, v24, v[96:111]
	v_mfma_f32_32x32x2_f32 v[96:111], v153, v25, v[96:111]
	v_mfma_f32_32x32x2_f32 v[96:111], v154, v26, v[96:111]
	v_mfma_f32_32x32x2_f32 v[96:111], v155, v27, v[96:111]
	v_mfma_f32_32x32x2_f32 v[96:111], v156, v28, v[96:111]
	v_mfma_f32_32x32x2_f32 v[96:111], v157, v29, v[96:111]
	v_mfma_f32_32x32x2_f32 v[96:111], v158, v30, v[96:111]
	v_mfma_f32_32x32x2_f32 v[96:111], v159, v31, v[96:111]
	s_add_i32 s30, s29, 0
	v_add_u32_e32 v119, s30, v118
	v_cvt_f32_u32_e32 v119, v119
	v_fmamk_f32 v119, v119, 0xbc83298c, v120
	v_mul_f32_e64 v119, v117, |v119|
	v_mul_f32_e32 v119, 0x3fb8aa3b, v119
	v_exp_f32_e32 v160, v119
	s_add_i32 s30, s29, 1
	v_add_u32_e32 v119, s30, v118
	v_cvt_f32_u32_e32 v119, v119
	v_fmamk_f32 v119, v119, 0xbc83298c, v120
	v_mul_f32_e64 v119, v117, |v119|
	v_mul_f32_e32 v119, 0x3fb8aa3b, v119
	v_exp_f32_e32 v161, v119
	s_add_i32 s30, s29, 2
	v_add_u32_e32 v119, s30, v118
	v_cvt_f32_u32_e32 v119, v119
	v_fmamk_f32 v119, v119, 0xbc83298c, v120
	v_mul_f32_e64 v119, v117, |v119|
	v_mul_f32_e32 v119, 0x3fb8aa3b, v119
	v_exp_f32_e32 v162, v119
	s_add_i32 s30, s29, 3
	v_add_u32_e32 v119, s30, v118
	v_cvt_f32_u32_e32 v119, v119
	v_fmamk_f32 v119, v119, 0xbc83298c, v120
	v_mul_f32_e64 v119, v117, |v119|
	v_mul_f32_e32 v119, 0x3fb8aa3b, v119
	v_exp_f32_e32 v163, v119
	s_add_i32 s30, s29, 8
	v_add_u32_e32 v119, s30, v118
	v_cvt_f32_u32_e32 v119, v119
	v_fmamk_f32 v119, v119, 0xbc83298c, v120
	v_mul_f32_e64 v119, v117, |v119|
	v_mul_f32_e32 v119, 0x3fb8aa3b, v119
	v_exp_f32_e32 v164, v119
	s_add_i32 s30, s29, 9
	v_add_u32_e32 v119, s30, v118
	v_cvt_f32_u32_e32 v119, v119
	v_fmamk_f32 v119, v119, 0xbc83298c, v120
	v_mul_f32_e64 v119, v117, |v119|
	v_mul_f32_e32 v119, 0x3fb8aa3b, v119
	v_exp_f32_e32 v165, v119
	s_add_i32 s30, s29, 10
	v_add_u32_e32 v119, s30, v118
	v_cvt_f32_u32_e32 v119, v119
	v_fmamk_f32 v119, v119, 0xbc83298c, v120
	v_mul_f32_e64 v119, v117, |v119|
	v_mul_f32_e32 v119, 0x3fb8aa3b, v119
	v_exp_f32_e32 v166, v119
	s_add_i32 s30, s29, 11
	v_add_u32_e32 v119, s30, v118
	v_cvt_f32_u32_e32 v119, v119
	v_fmamk_f32 v119, v119, 0xbc83298c, v120
	v_mul_f32_e64 v119, v117, |v119|
	v_mul_f32_e32 v119, 0x3fb8aa3b, v119
	v_exp_f32_e32 v167, v119
	s_add_i32 s30, s29, 16
	v_add_u32_e32 v119, s30, v118
	v_cvt_f32_u32_e32 v119, v119
	v_fmamk_f32 v119, v119, 0xbc83298c, v120
	v_mul_f32_e64 v119, v117, |v119|
	v_mul_f32_e32 v119, 0x3fb8aa3b, v119
	v_exp_f32_e32 v168, v119
	s_add_i32 s30, s29, 17
	v_add_u32_e32 v119, s30, v118
	v_cvt_f32_u32_e32 v119, v119
	v_fmamk_f32 v119, v119, 0xbc83298c, v120
	v_mul_f32_e64 v119, v117, |v119|
	v_mul_f32_e32 v119, 0x3fb8aa3b, v119
	v_exp_f32_e32 v169, v119
	s_add_i32 s30, s29, 18
	v_add_u32_e32 v119, s30, v118
	v_cvt_f32_u32_e32 v119, v119
	v_fmamk_f32 v119, v119, 0xbc83298c, v120
	v_mul_f32_e64 v119, v117, |v119|
	v_mul_f32_e32 v119, 0x3fb8aa3b, v119
	v_exp_f32_e32 v170, v119
	s_add_i32 s30, s29, 19
	v_add_u32_e32 v119, s30, v118
	v_cvt_f32_u32_e32 v119, v119
	v_fmamk_f32 v119, v119, 0xbc83298c, v120
	v_mul_f32_e64 v119, v117, |v119|
	v_mul_f32_e32 v119, 0x3fb8aa3b, v119
	v_exp_f32_e32 v171, v119
	s_add_i32 s30, s29, 24
	v_add_u32_e32 v119, s30, v118
	v_cvt_f32_u32_e32 v119, v119
	v_fmamk_f32 v119, v119, 0xbc83298c, v120
	v_mul_f32_e64 v119, v117, |v119|
	v_mul_f32_e32 v119, 0x3fb8aa3b, v119
	v_exp_f32_e32 v172, v119
	s_add_i32 s30, s29, 25
	v_add_u32_e32 v119, s30, v118
	v_cvt_f32_u32_e32 v119, v119
	v_fmamk_f32 v119, v119, 0xbc83298c, v120
	v_mul_f32_e64 v119, v117, |v119|
	v_mul_f32_e32 v119, 0x3fb8aa3b, v119
	v_exp_f32_e32 v173, v119
	s_add_i32 s30, s29, 26
	v_add_u32_e32 v119, s30, v118
	v_cvt_f32_u32_e32 v119, v119
	v_fmamk_f32 v119, v119, 0xbc83298c, v120
	v_mul_f32_e64 v119, v117, |v119|
	v_mul_f32_e32 v119, 0x3fb8aa3b, v119
	v_exp_f32_e32 v174, v119
	s_add_i32 s30, s29, 27
	v_add_u32_e32 v119, s30, v118
	v_cvt_f32_u32_e32 v119, v119
	v_fmamk_f32 v119, v119, 0xbc83298c, v120
	v_mul_f32_e64 v119, v117, |v119|
	v_mul_f32_e32 v119, 0x3fb8aa3b, v119
	v_exp_f32_e32 v175, v119
	s_nop 7
	v_mul_f32_e32 v176, v96, v160
	s_mov_b64 s[36:37], s[34:35]
	global_store_dword v115, v176, s[36:37] nt
	v_mul_f32_e32 v177, v97, v161
	s_add_u32 s36, s34, 0xc000
	s_addc_u32 s37, s35, 0
	global_store_dword v115, v177, s[36:37] nt
	v_mul_f32_e32 v178, v98, v162
; __device__ __forceinline__ void kraw_items(const Args& a, int gw, int NGW, int lane) {
;     ...
;             for (int ci = 0; ci < 12; ++ci) { const int c = c0 + 12 * cb + ci;
;                 float acc = 0.f;
; #pragma unroll
;                 for (int jj = 0; jj < 64; ++jj) acc += h[jj] * __builtin_bit_cast(float, __builtin_amdgcn_readlane(__builtin_bit_cast(int, wv[ci]), jj));
;                 const int cm = c % 768;
;                 const float delta = fabsf(-3.0701134573253945f + (float)cm * ((-15.350567286626973f + 3.0701134573253945f) / 767.0f));
;                 KR[(size_t)c * (LP + LS) + p] = acc * __expf(-tt * delta); }
	s_add_u32 s36, s34, 0x18000
	s_addc_u32 s37, s35, 0
	global_store_dword v115, v178, s[36:37] nt
	v_mul_f32_e32 v179, v99, v163
	s_add_u32 s36, s34, 0x24000
	s_addc_u32 s37, s35, 0
	global_store_dword v115, v179, s[36:37] nt
	v_mul_f32_e32 v180, v100, v164
	s_add_u32 s36, s34, 0x60000
	s_addc_u32 s37, s35, 0
	global_store_dword v115, v180, s[36:37] nt
	v_mul_f32_e32 v181, v101, v165
	s_add_u32 s36, s34, 0x6c000
	s_addc_u32 s37, s35, 0
	global_store_dword v115, v181, s[36:37] nt
	v_mul_f32_e32 v182, v102, v166
	s_add_u32 s36, s34, 0x78000
	s_addc_u32 s37, s35, 0
	global_store_dword v115, v182, s[36:37] nt
	v_mul_f32_e32 v183, v103, v167
	s_add_u32 s36, s34, 0x84000
	s_addc_u32 s37, s35, 0
	global_store_dword v115, v183, s[36:37] nt
	v_mul_f32_e32 v184, v104, v168
	s_add_u32 s36, s34, 0xc0000
	s_addc_u32 s37, s35, 0
	global_store_dword v115, v184, s[36:37] nt
	v_mul_f32_e32 v185, v105, v169
	s_add_u32 s36, s34, 0xcc000
	s_addc_u32 s37, s35, 0
	global_store_dword v115, v185, s[36:37] nt
	v_mul_f32_e32 v186, v106, v170
	s_add_u32 s36, s34, 0xd8000
	s_addc_u32 s37, s35, 0
	global_store_dword v115, v186, s[36:37] nt
	v_mul_f32_e32 v187, v107, v171
	s_add_u32 s36, s34, 0xe4000
	s_addc_u32 s37, s35, 0
	global_store_dword v115, v187, s[36:37] nt
	v_mul_f32_e32 v188, v108, v172
	s_add_u32 s36, s34, 0x120000
	s_addc_u32 s37, s35, 0
	global_store_dword v115, v188, s[36:37] nt
	v_mul_f32_e32 v189, v109, v173
	s_add_u32 s36, s34, 0x12c000
	s_addc_u32 s37, s35, 0
	global_store_dword v115, v189, s[36:37] nt
	v_mul_f32_e32 v190, v110, v174
	s_add_u32 s36, s34, 0x138000
	s_addc_u32 s37, s35, 0
	global_store_dword v115, v190, s[36:37] nt
	v_mul_f32_e32 v191, v111, v175
	s_add_u32 s36, s34, 0x144000
	s_addc_u32 s37, s35, 0
	global_store_dword v115, v191, s[36:37] nt
	s_add_i32 s28, s21, 64
	s_sub_i32 s29, s28, 0x300
	s_cmp_ge_u32 s28, 0x300
	s_cselect_b32 s29, s29, s28
	s_mul_i32 s30, s28, 0xc000
	s_lshl_b32 s35, s20, 2
	s_add_u32 s30, s30, s35
	s_add_u32 s34, s14, s30
	s_addc_u32 s35, s15, 0
	s_waitcnt vmcnt(16)
	v_mfma_f32_32x32x2_f32 v[96:111], v64, v0, 0
	v_mfma_f32_32x32x2_f32 v[96:111], v65, v1, v[96:111]
	v_mfma_f32_32x32x2_f32 v[96:111], v66, v2, v[96:111]
	v_mfma_f32_32x32x2_f32 v[96:111], v67, v3, v[96:111]
	v_mfma_f32_32x32x2_f32 v[96:111], v68, v4, v[96:111]
	v_mfma_f32_32x32x2_f32 v[96:111], v69, v5, v[96:111]
	v_mfma_f32_32x32x2_f32 v[96:111], v70, v6, v[96:111]
	v_mfma_f32_32x32x2_f32 v[96:111], v71, v7, v[96:111]
	v_mfma_f32_32x32x2_f32 v[96:111], v72, v8, v[96:111]
	v_mfma_f32_32x32x2_f32 v[96:111], v73, v9, v[96:111]
	v_mfma_f32_32x32x2_f32 v[96:111], v74, v10, v[96:111]
	v_mfma_f32_32x32x2_f32 v[96:111], v75, v11, v[96:111]
	v_mfma_f32_32x32x2_f32 v[96:111], v76, v12, v[96:111]
	v_mfma_f32_32x32x2_f32 v[96:111], v77, v13, v[96:111]
	v_mfma_f32_32x32x2_f32 v[96:111], v78, v14, v[96:111]
	v_mfma_f32_32x32x2_f32 v[96:111], v79, v15, v[96:111]
	v_mfma_f32_32x32x2_f32 v[96:111], v80, v16, v[96:111]
	v_mfma_f32_32x32x2_f32 v[96:111], v81, v17, v[96:111]
	v_mfma_f32_32x32x2_f32 v[96:111], v82, v18, v[96:111]
	v_mfma_f32_32x32x2_f32 v[96:111], v83, v19, v[96:111]
	v_mfma_f32_32x32x2_f32 v[96:111], v84, v20, v[96:111]
	v_mfma_f32_32x32x2_f32 v[96:111], v85, v21, v[96:111]
	v_mfma_f32_32x32x2_f32 v[96:111], v86, v22, v[96:111]
	v_mfma_f32_32x32x2_f32 v[96:111], v87, v23, v[96:111]
	v_mfma_f32_32x32x2_f32 v[96:111], v88, v24, v[96:111]
	v_mfma_f32_32x32x2_f32 v[96:111], v89, v25, v[96:111]
	v_mfma_f32_32x32x2_f32 v[96:111], v90, v26, v[96:111]
	v_mfma_f32_32x32x2_f32 v[96:111], v91, v27, v[96:111]
	v_mfma_f32_32x32x2_f32 v[96:111], v92, v28, v[96:111]
	v_mfma_f32_32x32x2_f32 v[96:111], v93, v29, v[96:111]
	v_mfma_f32_32x32x2_f32 v[96:111], v94, v30, v[96:111]
	v_mfma_f32_32x32x2_f32 v[96:111], v95, v31, v[96:111]
	s_add_i32 s30, s29, 0
	v_add_u32_e32 v119, s30, v118
	v_cvt_f32_u32_e32 v119, v119
	v_fmamk_f32 v119, v119, 0xbc83298c, v120
	v_mul_f32_e64 v119, v117, |v119|
	v_mul_f32_e32 v119, 0x3fb8aa3b, v119
	v_exp_f32_e32 v160, v119
	s_add_i32 s30, s29, 1
	v_add_u32_e32 v119, s30, v118
	v_cvt_f32_u32_e32 v119, v119
	v_fmamk_f32 v119, v119, 0xbc83298c, v120
	v_mul_f32_e64 v119, v117, |v119|
	v_mul_f32_e32 v119, 0x3fb8aa3b, v119
	v_exp_f32_e32 v161, v119
	s_add_i32 s30, s29, 2
	v_add_u32_e32 v119, s30, v118
	v_cvt_f32_u32_e32 v119, v119
	v_fmamk_f32 v119, v119, 0xbc83298c, v120
	v_mul_f32_e64 v119, v117, |v119|
	v_mul_f32_e32 v119, 0x3fb8aa3b, v119
	v_exp_f32_e32 v162, v119
	s_add_i32 s30, s29, 3
	v_add_u32_e32 v119, s30, v118
	v_cvt_f32_u32_e32 v119, v119
	v_fmamk_f32 v119, v119, 0xbc83298c, v120
	v_mul_f32_e64 v119, v117, |v119|
	v_mul_f32_e32 v119, 0x3fb8aa3b, v119
	v_exp_f32_e32 v163, v119
	s_add_i32 s30, s29, 8
	v_add_u32_e32 v119, s30, v118
; __device__ __forceinline__ void kraw_items(const Args& a, int gw, int NGW, int lane) {
;     ...
;                 const float delta = fabsf(-3.0701134573253945f + (float)cm * ((-15.350567286626973f + 3.0701134573253945f) / 767.0f));
;                 KR[(size_t)c * (LP + LS) + p] = acc * __expf(-tt * delta); }
	v_cvt_f32_u32_e32 v119, v119
	v_fmamk_f32 v119, v119, 0xbc83298c, v120
	v_mul_f32_e64 v119, v117, |v119|
	v_mul_f32_e32 v119, 0x3fb8aa3b, v119
	v_exp_f32_e32 v164, v119
	s_add_i32 s30, s29, 9
	v_add_u32_e32 v119, s30, v118
	v_cvt_f32_u32_e32 v119, v119
	v_fmamk_f32 v119, v119, 0xbc83298c, v120
	v_mul_f32_e64 v119, v117, |v119|
	v_mul_f32_e32 v119, 0x3fb8aa3b, v119
	v_exp_f32_e32 v165, v119
	s_add_i32 s30, s29, 10
	v_add_u32_e32 v119, s30, v118
	v_cvt_f32_u32_e32 v119, v119
	v_fmamk_f32 v119, v119, 0xbc83298c, v120
	v_mul_f32_e64 v119, v117, |v119|
	v_mul_f32_e32 v119, 0x3fb8aa3b, v119
	v_exp_f32_e32 v166, v119
	s_add_i32 s30, s29, 11
	v_add_u32_e32 v119, s30, v118
	v_cvt_f32_u32_e32 v119, v119
	v_fmamk_f32 v119, v119, 0xbc83298c, v120
	v_mul_f32_e64 v119, v117, |v119|
	v_mul_f32_e32 v119, 0x3fb8aa3b, v119
	v_exp_f32_e32 v167, v119
	s_add_i32 s30, s29, 16
	v_add_u32_e32 v119, s30, v118
	v_cvt_f32_u32_e32 v119, v119
	v_fmamk_f32 v119, v119, 0xbc83298c, v120
	v_mul_f32_e64 v119, v117, |v119|
	v_mul_f32_e32 v119, 0x3fb8aa3b, v119
	v_exp_f32_e32 v168, v119
	s_add_i32 s30, s29, 17
	v_add_u32_e32 v119, s30, v118
	v_cvt_f32_u32_e32 v119, v119
	v_fmamk_f32 v119, v119, 0xbc83298c, v120
	v_mul_f32_e64 v119, v117, |v119|
	v_mul_f32_e32 v119, 0x3fb8aa3b, v119
	v_exp_f32_e32 v169, v119
	s_add_i32 s30, s29, 18
	v_add_u32_e32 v119, s30, v118
	v_cvt_f32_u32_e32 v119, v119
	v_fmamk_f32 v119, v119, 0xbc83298c, v120
	v_mul_f32_e64 v119, v117, |v119|
	v_mul_f32_e32 v119, 0x3fb8aa3b, v119
	v_exp_f32_e32 v170, v119
	s_add_i32 s30, s29, 19
	v_add_u32_e32 v119, s30, v118
	v_cvt_f32_u32_e32 v119, v119
	v_fmamk_f32 v119, v119, 0xbc83298c, v120
	v_mul_f32_e64 v119, v117, |v119|
	v_mul_f32_e32 v119, 0x3fb8aa3b, v119
	v_exp_f32_e32 v171, v119
	s_add_i32 s30, s29, 24
	v_add_u32_e32 v119, s30, v118
	v_cvt_f32_u32_e32 v119, v119
	v_fmamk_f32 v119, v119, 0xbc83298c, v120
	v_mul_f32_e64 v119, v117, |v119|
	v_mul_f32_e32 v119, 0x3fb8aa3b, v119
	v_exp_f32_e32 v172, v119
	s_add_i32 s30, s29, 25
	v_add_u32_e32 v119, s30, v118
	v_cvt_f32_u32_e32 v119, v119
	v_fmamk_f32 v119, v119, 0xbc83298c, v120
	v_mul_f32_e64 v119, v117, |v119|
	v_mul_f32_e32 v119, 0x3fb8aa3b, v119
	v_exp_f32_e32 v173, v119
	s_add_i32 s30, s29, 26
	v_add_u32_e32 v119, s30, v118
	v_cvt_f32_u32_e32 v119, v119
	v_fmamk_f32 v119, v119, 0xbc83298c, v120
	v_mul_f32_e64 v119, v117, |v119|
	v_mul_f32_e32 v119, 0x3fb8aa3b, v119
	v_exp_f32_e32 v174, v119
	s_add_i32 s30, s29, 27
	v_add_u32_e32 v119, s30, v118
	v_cvt_f32_u32_e32 v119, v119
	v_fmamk_f32 v119, v119, 0xbc83298c, v120
	v_mul_f32_e64 v119, v117, |v119|
	v_mul_f32_e32 v119, 0x3fb8aa3b, v119
	v_exp_f32_e32 v175, v119
	s_nop 7
	v_mul_f32_e32 v176, v96, v160
	s_mov_b64 s[36:37], s[34:35]
	global_store_dword v115, v176, s[36:37] nt
	v_mul_f32_e32 v177, v97, v161
	s_add_u32 s36, s34, 0xc000
	s_addc_u32 s37, s35, 0
	global_store_dword v115, v177, s[36:37] nt
	v_mul_f32_e32 v178, v98, v162
	s_add_u32 s36, s34, 0x18000
	s_addc_u32 s37, s35, 0
	global_store_dword v115, v178, s[36:37] nt
	v_mul_f32_e32 v179, v99, v163
	s_add_u32 s36, s34, 0x24000
	s_addc_u32 s37, s35, 0
	global_store_dword v115, v179, s[36:37] nt
	v_mul_f32_e32 v180, v100, v164
	s_add_u32 s36, s34, 0x60000
	s_addc_u32 s37, s35, 0
	global_store_dword v115, v180, s[36:37] nt
	v_mul_f32_e32 v181, v101, v165
	s_add_u32 s36, s34, 0x6c000
	s_addc_u32 s37, s35, 0
	global_store_dword v115, v181, s[36:37] nt
	v_mul_f32_e32 v182, v102, v166
	s_add_u32 s36, s34, 0x78000
	s_addc_u32 s37, s35, 0
	global_store_dword v115, v182, s[36:37] nt
	v_mul_f32_e32 v183, v103, v167
	s_add_u32 s36, s34, 0x84000
	s_addc_u32 s37, s35, 0
	global_store_dword v115, v183, s[36:37] nt
	v_mul_f32_e32 v184, v104, v168
	s_add_u32 s36, s34, 0xc0000
	s_addc_u32 s37, s35, 0
	global_store_dword v115, v184, s[36:37] nt
	v_mul_f32_e32 v185, v105, v169
	s_add_u32 s36, s34, 0xcc000
	s_addc_u32 s37, s35, 0
	global_store_dword v115, v185, s[36:37] nt
	v_mul_f32_e32 v186, v106, v170
	s_add_u32 s36, s34, 0xd8000
	s_addc_u32 s37, s35, 0
	global_store_dword v115, v186, s[36:37] nt
	v_mul_f32_e32 v187, v107, v171
	s_add_u32 s36, s34, 0xe4000
	s_addc_u32 s37, s35, 0
	global_store_dword v115, v187, s[36:37] nt
	v_mul_f32_e32 v188, v108, v172
	s_add_u32 s36, s34, 0x120000
	s_addc_u32 s37, s35, 0
	global_store_dword v115, v188, s[36:37] nt
	v_mul_f32_e32 v189, v109, v173
	s_add_u32 s36, s34, 0x12c000
	s_addc_u32 s37, s35, 0
	global_store_dword v115, v189, s[36:37] nt
	v_mul_f32_e32 v190, v110, v174
	s_add_u32 s36, s34, 0x138000
	s_addc_u32 s37, s35, 0
	global_store_dword v115, v190, s[36:37] nt
	v_mul_f32_e32 v191, v111, v175
	s_add_u32 s36, s34, 0x144000
	s_addc_u32 s37, s35, 0
	global_store_dword v115, v191, s[36:37] nt
	s_branch .LBB0_122
